# S phase: first four SS rows of the softmax epilogue fetched during the last K trip (copy of the loop body with counted waits +5); rows 4-7 scale chain deferred
# baseline (speedup 1.0000x reference)
.LBB0_514:
	ds_read_b128 v[146:149], v170
	ds_read_b128 v[150:153], v170 offset:1024
	ds_read_b128 v[154:157], v170 offset:2048
	ds_read_b128 v[158:161], v170 offset:3072
	ds_read_b128 v[162:165], v171
	ds_read_b128 v[182:185], v171 offset:1024
	ds_read_b128 v[186:189], v171 offset:2048
	ds_read_b128 v[190:193], v171 offset:3072
	s_add_u32 s35, s36, 0xfffc0080
	s_addc_u32 s38, s37, -1
	s_cmp_eq_u32 s33, 12
	s_cselect_b32 s41, s29, s38
	s_cselect_b32 s40, s28, s35
	s_cselect_b32 s39, s31, s23
	s_cselect_b32 s38, s30, s21
	v_lshl_add_u64 v[198:199], s[36:37], 0, v[138:139]
	s_add_i32 m0, s13, 0xc000
	ds_read_b128 v[194:197], v172
	ds_read_b128 v[202:205], v172 offset:1024
	ds_read_b128 v[206:209], v172 offset:2048
	ds_read_b128 v[210:213], v172 offset:3072
	ds_read_b128 v[214:217], v172 offset:4096
	ds_read_b128 v[218:221], v172 offset:5120
	ds_read_b128 v[222:225], v172 offset:6144
	ds_read_b128 v[226:229], v172 offset:7168
	global_load_lds_dwordx4 v[198:199], off
	v_lshl_add_u64 v[198:199], s[36:37], 0, v[140:141]
	s_add_i32 m0, s13, 0xe000
	s_nop 0
	global_load_lds_dwordx4 v[198:199], off
	s_waitcnt vmcnt(8)
	s_waitcnt lgkmcnt(0)
	s_barrier
	s_setprio 1
	s_waitcnt lgkmcnt(0)
	v_mfma_f32_16x16x32_bf16 v[124:127], v[146:149], v[194:197], v[124:127]
	v_mfma_f32_16x16x32_bf16 v[120:123], v[154:157], v[194:197], v[120:123]
	v_mfma_f32_16x16x32_bf16 v[108:111], v[146:149], v[206:209], v[108:111]
	v_mfma_f32_16x16x32_bf16 v[104:107], v[154:157], v[206:209], v[104:107]
	v_mfma_f32_16x16x32_bf16 v[92:95], v[146:149], v[214:217], v[92:95]
	v_mfma_f32_16x16x32_bf16 v[88:91], v[154:157], v[214:217], v[88:91]
	v_mfma_f32_16x16x32_bf16 v[76:79], v[146:149], v[222:225], v[76:79]
	v_mfma_f32_16x16x32_bf16 v[72:75], v[154:157], v[222:225], v[72:75]
	v_mfma_f32_16x16x32_bf16 v[124:127], v[150:153], v[202:205], v[124:127]
	v_mfma_f32_16x16x32_bf16 v[120:123], v[158:161], v[202:205], v[120:123]
	v_mfma_f32_16x16x32_bf16 v[108:111], v[150:153], v[210:213], v[108:111]
	v_mfma_f32_16x16x32_bf16 v[104:107], v[158:161], v[210:213], v[104:107]
	v_mfma_f32_16x16x32_bf16 v[92:95], v[150:153], v[218:221], v[92:95]
	v_mfma_f32_16x16x32_bf16 v[88:91], v[158:161], v[218:221], v[88:91]
	v_mfma_f32_16x16x32_bf16 v[76:79], v[150:153], v[226:229], v[76:79]
	v_mfma_f32_16x16x32_bf16 v[72:75], v[158:161], v[226:229], v[72:75]
	s_setprio 0
	s_setprio 1
	v_mfma_f32_16x16x32_bf16 v[116:119], v[162:165], v[194:197], v[116:119]
	v_mfma_f32_16x16x32_bf16 v[112:115], v[186:189], v[194:197], v[112:115]
	v_mfma_f32_16x16x32_bf16 v[100:103], v[162:165], v[206:209], v[100:103]
	v_mfma_f32_16x16x32_bf16 v[96:99], v[186:189], v[206:209], v[96:99]
	v_mfma_f32_16x16x32_bf16 v[84:87], v[162:165], v[214:217], v[84:87]
	v_mfma_f32_16x16x32_bf16 v[80:83], v[186:189], v[214:217], v[80:83]
	v_mfma_f32_16x16x32_bf16 v[68:71], v[162:165], v[222:225], v[68:71]
	v_mfma_f32_16x16x32_bf16 v[64:67], v[186:189], v[222:225], v[64:67]
	v_mfma_f32_16x16x32_bf16 v[116:119], v[182:185], v[202:205], v[116:119]
	v_mfma_f32_16x16x32_bf16 v[112:115], v[190:193], v[202:205], v[112:115]
	v_mfma_f32_16x16x32_bf16 v[100:103], v[182:185], v[210:213], v[100:103]
	v_mfma_f32_16x16x32_bf16 v[96:99], v[190:193], v[210:213], v[96:99]
	v_mfma_f32_16x16x32_bf16 v[84:87], v[182:185], v[218:221], v[84:87]
	v_mfma_f32_16x16x32_bf16 v[80:83], v[190:193], v[218:221], v[80:83]
	v_mfma_f32_16x16x32_bf16 v[68:71], v[182:185], v[226:229], v[68:71]
	v_mfma_f32_16x16x32_bf16 v[64:67], v[190:193], v[226:229], v[64:67]
	s_setprio 0
	s_barrier
	s_add_i32 s35, s54, s9
	v_lshl_add_u64 v[198:199], s[38:39], 0, v[130:131]
	s_mov_b32 m0, s35
	ds_read_b128 v[194:197], v172 offset:16384
	ds_read_b128 v[202:205], v172 offset:17408
	ds_read_b128 v[206:209], v172 offset:18432
	ds_read_b128 v[210:213], v172 offset:19456
	ds_read_b128 v[214:217], v172 offset:20480
	ds_read_b128 v[218:221], v172 offset:21504
	ds_read_b128 v[222:225], v172 offset:22528
	ds_read_b128 v[226:229], v172 offset:23552
	global_load_lds_dwordx4 v[198:199], off
	s_add_i32 m0, s35, 0x2000
	s_add_u32 s58, s38, 0x40000
	v_lshl_add_u64 v[230:231], s[38:39], 0, v[134:135]
	s_addc_u32 s59, s39, 0
	s_add_i32 s35, s55, s9
	global_load_lds_dwordx4 v[230:231], off
	v_lshl_add_u64 v[232:233], s[58:59], 0, v[130:131]
	s_mov_b32 m0, s35
	v_lshl_add_u64 v[234:235], s[40:41], 0, v[132:133]
	global_load_lds_dwordx4 v[232:233], off
	v_lshl_add_u64 v[232:233], s[58:59], 0, v[134:135]
	s_add_i32 m0, s35, 0x2000
	s_nop 0
	global_load_lds_dwordx4 v[232:233], off
	v_lshl_add_u64 v[232:233], s[40:41], 0, v[128:129]
	s_mov_b32 m0, s13
	s_nop 0
	global_load_lds_dwordx4 v[232:233], off
	s_mov_b32 m0, s43
	s_nop 0
	global_load_lds_dwordx4 v[234:235], off
	s_waitcnt vmcnt(8)
	s_waitcnt lgkmcnt(0)
	s_barrier
	s_setprio 1
	s_waitcnt lgkmcnt(0)
	v_mfma_f32_16x16x32_bf16 v[60:63], v[146:149], v[194:197], v[60:63]
	v_mfma_f32_16x16x32_bf16 v[56:59], v[154:157], v[194:197], v[56:59]
	v_mfma_f32_16x16x32_bf16 v[44:47], v[146:149], v[206:209], v[44:47]
	v_mfma_f32_16x16x32_bf16 v[40:43], v[154:157], v[206:209], v[40:43]
	v_mfma_f32_16x16x32_bf16 v[28:31], v[146:149], v[214:217], v[28:31]
	v_mfma_f32_16x16x32_bf16 v[24:27], v[154:157], v[214:217], v[24:27]
	v_mfma_f32_16x16x32_bf16 v[12:15], v[146:149], v[222:225], v[12:15]
	v_mfma_f32_16x16x32_bf16 v[8:11], v[154:157], v[222:225], v[8:11]
	v_mfma_f32_16x16x32_bf16 v[60:63], v[150:153], v[202:205], v[60:63]
	v_mfma_f32_16x16x32_bf16 v[56:59], v[158:161], v[202:205], v[56:59]
	v_mfma_f32_16x16x32_bf16 v[44:47], v[150:153], v[210:213], v[44:47]
	v_mfma_f32_16x16x32_bf16 v[40:43], v[158:161], v[210:213], v[40:43]
	v_mfma_f32_16x16x32_bf16 v[28:31], v[150:153], v[218:221], v[28:31]
	v_mfma_f32_16x16x32_bf16 v[24:27], v[158:161], v[218:221], v[24:27]
	v_mfma_f32_16x16x32_bf16 v[12:15], v[150:153], v[226:229], v[12:15]
	v_mfma_f32_16x16x32_bf16 v[8:11], v[158:161], v[226:229], v[8:11]
	s_setprio 0
	s_setprio 1
	v_mfma_f32_16x16x32_bf16 v[52:55], v[162:165], v[194:197], v[52:55]
	v_mfma_f32_16x16x32_bf16 v[48:51], v[186:189], v[194:197], v[48:51]
	v_mfma_f32_16x16x32_bf16 v[36:39], v[162:165], v[206:209], v[36:39]
	v_mfma_f32_16x16x32_bf16 v[32:35], v[186:189], v[206:209], v[32:35]
	v_mfma_f32_16x16x32_bf16 v[20:23], v[162:165], v[214:217], v[20:23]
	v_mfma_f32_16x16x32_bf16 v[16:19], v[186:189], v[214:217], v[16:19]
	v_mfma_f32_16x16x32_bf16 v[4:7], v[162:165], v[222:225], v[4:7]
	v_mfma_f32_16x16x32_bf16 v[0:3], v[186:189], v[222:225], v[0:3]
	v_mfma_f32_16x16x32_bf16 v[52:55], v[182:185], v[202:205], v[52:55]
	v_mfma_f32_16x16x32_bf16 v[48:51], v[190:193], v[202:205], v[48:51]
	v_mfma_f32_16x16x32_bf16 v[36:39], v[182:185], v[210:213], v[36:39]
	v_mfma_f32_16x16x32_bf16 v[32:35], v[190:193], v[210:213], v[32:35]
	v_mfma_f32_16x16x32_bf16 v[20:23], v[182:185], v[218:221], v[20:23]
	v_mfma_f32_16x16x32_bf16 v[16:19], v[190:193], v[218:221], v[16:19]
	v_mfma_f32_16x16x32_bf16 v[4:7], v[182:185], v[226:229], v[4:7]
	v_mfma_f32_16x16x32_bf16 v[0:3], v[190:193], v[226:229], v[0:3]
	s_setprio 0
	s_barrier
	s_add_i32 s35, 0, 0x18000
	s_add_i32 s58, 0, 0x1c000
	v_add_u32_e32 v158, s35, v167
	v_add_u32_e32 v190, s58, v167
	ds_read_b128 v[146:149], v158
	ds_read_b128 v[150:153], v158 offset:1024
	ds_read_b128 v[154:157], v158 offset:2048
	ds_read_b128 v[158:161], v158 offset:3072
	ds_read_b128 v[162:165], v190
	ds_read_b128 v[182:185], v190 offset:1024
	ds_read_b128 v[186:189], v190 offset:2048
	ds_read_b128 v[190:193], v190 offset:3072
	s_add_u32 s40, s40, 0x40000
	s_addc_u32 s41, s41, 0
	s_mov_b32 m0, s45
	v_lshl_add_u64 v[236:237], s[40:41], 0, v[128:129]
	ds_read_b128 v[194:197], v172 offset:32768
	ds_read_b128 v[202:205], v172 offset:33792
	ds_read_b128 v[206:209], v172 offset:34816
	ds_read_b128 v[210:213], v172 offset:35840
	ds_read_b128 v[214:217], v172 offset:36864
	ds_read_b128 v[218:221], v172 offset:37888
	ds_read_b128 v[222:225], v172 offset:38912
	ds_read_b128 v[226:229], v172 offset:39936
	global_load_lds_dwordx4 v[236:237], off
	v_lshl_add_u64 v[236:237], s[40:41], 0, v[132:133]
	s_mov_b32 m0, s46
	s_nop 0
	global_load_lds_dwordx4 v[236:237], off
	s_waitcnt vmcnt(8)
	s_waitcnt lgkmcnt(0)
	s_barrier
	s_setprio 1
	s_waitcnt lgkmcnt(0)
	v_mfma_f32_16x16x32_bf16 v[124:127], v[146:149], v[194:197], v[124:127]
	v_mfma_f32_16x16x32_bf16 v[120:123], v[154:157], v[194:197], v[120:123]
	v_mfma_f32_16x16x32_bf16 v[108:111], v[146:149], v[206:209], v[108:111]
	v_mfma_f32_16x16x32_bf16 v[104:107], v[154:157], v[206:209], v[104:107]
	v_mfma_f32_16x16x32_bf16 v[92:95], v[146:149], v[214:217], v[92:95]
	v_mfma_f32_16x16x32_bf16 v[88:91], v[154:157], v[214:217], v[88:91]
	v_mfma_f32_16x16x32_bf16 v[76:79], v[146:149], v[222:225], v[76:79]
	v_mfma_f32_16x16x32_bf16 v[72:75], v[154:157], v[222:225], v[72:75]
	v_mfma_f32_16x16x32_bf16 v[124:127], v[150:153], v[202:205], v[124:127]
	v_mfma_f32_16x16x32_bf16 v[120:123], v[158:161], v[202:205], v[120:123]
	v_mfma_f32_16x16x32_bf16 v[108:111], v[150:153], v[210:213], v[108:111]
	v_mfma_f32_16x16x32_bf16 v[104:107], v[158:161], v[210:213], v[104:107]
	v_mfma_f32_16x16x32_bf16 v[92:95], v[150:153], v[218:221], v[92:95]
	v_mfma_f32_16x16x32_bf16 v[88:91], v[158:161], v[218:221], v[88:91]
	v_mfma_f32_16x16x32_bf16 v[76:79], v[150:153], v[226:229], v[76:79]
	v_mfma_f32_16x16x32_bf16 v[72:75], v[158:161], v[226:229], v[72:75]
	s_setprio 0
	s_setprio 1
	v_mfma_f32_16x16x32_bf16 v[116:119], v[162:165], v[194:197], v[116:119]
	v_mfma_f32_16x16x32_bf16 v[112:115], v[186:189], v[194:197], v[112:115]
	v_mfma_f32_16x16x32_bf16 v[100:103], v[162:165], v[206:209], v[100:103]
	v_mfma_f32_16x16x32_bf16 v[96:99], v[186:189], v[206:209], v[96:99]
	v_mfma_f32_16x16x32_bf16 v[84:87], v[162:165], v[214:217], v[84:87]
	v_mfma_f32_16x16x32_bf16 v[80:83], v[186:189], v[214:217], v[80:83]
	v_mfma_f32_16x16x32_bf16 v[68:71], v[162:165], v[222:225], v[68:71]
	v_mfma_f32_16x16x32_bf16 v[64:67], v[186:189], v[222:225], v[64:67]
	v_mfma_f32_16x16x32_bf16 v[116:119], v[182:185], v[202:205], v[116:119]
	v_mfma_f32_16x16x32_bf16 v[112:115], v[190:193], v[202:205], v[112:115]
	v_mfma_f32_16x16x32_bf16 v[100:103], v[182:185], v[210:213], v[100:103]
	v_mfma_f32_16x16x32_bf16 v[96:99], v[190:193], v[210:213], v[96:99]
	v_mfma_f32_16x16x32_bf16 v[84:87], v[182:185], v[218:221], v[84:87]
	v_mfma_f32_16x16x32_bf16 v[80:83], v[190:193], v[218:221], v[80:83]
	v_mfma_f32_16x16x32_bf16 v[68:71], v[182:185], v[226:229], v[68:71]
	v_mfma_f32_16x16x32_bf16 v[64:67], v[190:193], v[226:229], v[64:67]
	s_setprio 0
	s_barrier
	s_add_i32 s35, s35, s9
	v_lshl_add_u64 v[198:199], v[198:199], 0, s[10:11]
	s_mov_b32 m0, s35
	ds_read_b128 v[194:197], v172 offset:49152
	ds_read_b128 v[202:205], v172 offset:50176
	ds_read_b128 v[206:209], v172 offset:51200
	ds_read_b128 v[210:213], v172 offset:52224
	ds_read_b128 v[214:217], v172 offset:53248
	ds_read_b128 v[218:221], v172 offset:54272
	ds_read_b128 v[222:225], v172 offset:55296
	ds_read_b128 v[226:229], v172 offset:56320
	global_load_lds_dwordx4 v[198:199], off
	s_add_i32 m0, s35, 0x2000
	s_add_u32 s38, s38, 0x40080
	v_lshl_add_u64 v[198:199], v[230:231], 0, s[10:11]
	s_addc_u32 s39, s39, 0
	s_add_i32 s35, s58, s9
	global_load_lds_dwordx4 v[198:199], off
	v_lshl_add_u64 v[198:199], s[38:39], 0, v[130:131]
	s_mov_b32 m0, s35
	s_nop 0
	global_load_lds_dwordx4 v[198:199], off
	v_lshl_add_u64 v[198:199], s[38:39], 0, v[134:135]
	s_add_i32 m0, s35, 0x2000
	s_nop 0
	global_load_lds_dwordx4 v[198:199], off
	v_lshl_add_u64 v[198:199], v[232:233], 0, s[10:11]
	s_mov_b32 m0, s51
	s_nop 0
	global_load_lds_dwordx4 v[198:199], off
	v_lshl_add_u64 v[198:199], v[234:235], 0, s[10:11]
	s_mov_b32 m0, s52
	s_nop 0
	global_load_lds_dwordx4 v[198:199], off
	s_waitcnt vmcnt(8)
	s_waitcnt lgkmcnt(0)
	s_barrier
	s_setprio 1
	s_waitcnt lgkmcnt(0)
	v_mfma_f32_16x16x32_bf16 v[60:63], v[146:149], v[194:197], v[60:63]
	v_mfma_f32_16x16x32_bf16 v[56:59], v[154:157], v[194:197], v[56:59]
	v_mfma_f32_16x16x32_bf16 v[44:47], v[146:149], v[206:209], v[44:47]
	v_mfma_f32_16x16x32_bf16 v[40:43], v[154:157], v[206:209], v[40:43]
	v_mfma_f32_16x16x32_bf16 v[28:31], v[146:149], v[214:217], v[28:31]
	v_mfma_f32_16x16x32_bf16 v[24:27], v[154:157], v[214:217], v[24:27]
	v_mfma_f32_16x16x32_bf16 v[12:15], v[146:149], v[222:225], v[12:15]
	v_mfma_f32_16x16x32_bf16 v[8:11], v[154:157], v[222:225], v[8:11]
	v_mfma_f32_16x16x32_bf16 v[60:63], v[150:153], v[202:205], v[60:63]
	v_mfma_f32_16x16x32_bf16 v[56:59], v[158:161], v[202:205], v[56:59]
	v_mfma_f32_16x16x32_bf16 v[44:47], v[150:153], v[210:213], v[44:47]
	v_mfma_f32_16x16x32_bf16 v[40:43], v[158:161], v[210:213], v[40:43]
	v_mfma_f32_16x16x32_bf16 v[28:31], v[150:153], v[218:221], v[28:31]
	v_mfma_f32_16x16x32_bf16 v[24:27], v[158:161], v[218:221], v[24:27]
	v_mfma_f32_16x16x32_bf16 v[12:15], v[150:153], v[226:229], v[12:15]
	v_mfma_f32_16x16x32_bf16 v[8:11], v[158:161], v[226:229], v[8:11]
	s_setprio 0
	s_setprio 1
	v_mfma_f32_16x16x32_bf16 v[52:55], v[162:165], v[194:197], v[52:55]
	v_mfma_f32_16x16x32_bf16 v[48:51], v[186:189], v[194:197], v[48:51]
	v_mfma_f32_16x16x32_bf16 v[36:39], v[162:165], v[206:209], v[36:39]
	v_mfma_f32_16x16x32_bf16 v[32:35], v[186:189], v[206:209], v[32:35]
	v_mfma_f32_16x16x32_bf16 v[20:23], v[162:165], v[214:217], v[20:23]
	v_mfma_f32_16x16x32_bf16 v[16:19], v[186:189], v[214:217], v[16:19]
	v_mfma_f32_16x16x32_bf16 v[4:7], v[162:165], v[222:225], v[4:7]
	v_mfma_f32_16x16x32_bf16 v[0:3], v[186:189], v[222:225], v[0:3]
	v_mfma_f32_16x16x32_bf16 v[52:55], v[182:185], v[202:205], v[52:55]
	v_mfma_f32_16x16x32_bf16 v[48:51], v[190:193], v[202:205], v[48:51]
	v_mfma_f32_16x16x32_bf16 v[36:39], v[182:185], v[210:213], v[36:39]
	v_mfma_f32_16x16x32_bf16 v[32:35], v[190:193], v[210:213], v[32:35]
	v_mfma_f32_16x16x32_bf16 v[20:23], v[182:185], v[218:221], v[20:23]
	v_mfma_f32_16x16x32_bf16 v[16:19], v[190:193], v[218:221], v[16:19]
	v_mfma_f32_16x16x32_bf16 v[4:7], v[182:185], v[226:229], v[4:7]
	v_mfma_f32_16x16x32_bf16 v[0:3], v[190:193], v[226:229], v[0:3]
	s_setprio 0
	s_barrier
	s_add_i32 s33, s33, 2
	s_add_u32 s36, s36, 0x100
	s_addc_u32 s37, s37, 0
	s_add_u32 s21, s21, 0x100
	s_addc_u32 s23, s23, 0
	s_cmp_gt_u32 s33, 11
	s_cbranch_scc0 .LBB0_514
	v_lshl_add_u32 v254, s34, 8, v166
	v_lshlrev_b32_e32 v254, 6, v254
	v_add_co_u32_e32 v254, vcc, v136, v254
	s_nop 1
	v_addc_co_u32_e32 v255, vcc, 0, v137, vcc
	global_load_dwordx4 v[238:241], v[254:255], off
	global_load_dwordx4 v[242:245], v[254:255], off offset:1024
	global_load_dwordx4 v[250:253], v[254:255], off offset:2048
	global_load_dwordx2 v[246:247], v[254:255], off offset:3072
	global_load_dwordx2 v[254:255], v[254:255], off offset:3080
	ds_read_b128 v[146:149], v170
	ds_read_b128 v[150:153], v170 offset:1024
	ds_read_b128 v[154:157], v170 offset:2048
	ds_read_b128 v[158:161], v170 offset:3072
	ds_read_b128 v[162:165], v171
	ds_read_b128 v[182:185], v171 offset:1024
	ds_read_b128 v[186:189], v171 offset:2048
	ds_read_b128 v[190:193], v171 offset:3072
	s_add_u32 s35, s36, 0xfffc0080
	s_addc_u32 s38, s37, -1
	s_cmp_eq_u32 s33, 12
	s_cselect_b32 s41, s29, s38
	s_cselect_b32 s40, s28, s35
	s_cselect_b32 s39, s31, s23
	s_cselect_b32 s38, s30, s21
	v_lshl_add_u64 v[198:199], s[36:37], 0, v[138:139]
	s_add_i32 m0, s13, 0xc000
	ds_read_b128 v[194:197], v172
	ds_read_b128 v[202:205], v172 offset:1024
	ds_read_b128 v[206:209], v172 offset:2048
	ds_read_b128 v[210:213], v172 offset:3072
	ds_read_b128 v[214:217], v172 offset:4096
	ds_read_b128 v[218:221], v172 offset:5120
	ds_read_b128 v[222:225], v172 offset:6144
	ds_read_b128 v[226:229], v172 offset:7168
	global_load_lds_dwordx4 v[198:199], off
	v_lshl_add_u64 v[198:199], s[36:37], 0, v[140:141]
	s_add_i32 m0, s13, 0xe000
	s_nop 0
	global_load_lds_dwordx4 v[198:199], off
	s_waitcnt vmcnt(13)
	s_waitcnt lgkmcnt(0)
	s_barrier
	s_setprio 1
	s_waitcnt lgkmcnt(0)
	v_mfma_f32_16x16x32_bf16 v[124:127], v[146:149], v[194:197], v[124:127]
	v_mfma_f32_16x16x32_bf16 v[120:123], v[154:157], v[194:197], v[120:123]
	v_mfma_f32_16x16x32_bf16 v[108:111], v[146:149], v[206:209], v[108:111]
	v_mfma_f32_16x16x32_bf16 v[104:107], v[154:157], v[206:209], v[104:107]
	v_mfma_f32_16x16x32_bf16 v[92:95], v[146:149], v[214:217], v[92:95]
	v_mfma_f32_16x16x32_bf16 v[88:91], v[154:157], v[214:217], v[88:91]
	v_mfma_f32_16x16x32_bf16 v[76:79], v[146:149], v[222:225], v[76:79]
	v_mfma_f32_16x16x32_bf16 v[72:75], v[154:157], v[222:225], v[72:75]
	v_mfma_f32_16x16x32_bf16 v[124:127], v[150:153], v[202:205], v[124:127]
	v_mfma_f32_16x16x32_bf16 v[120:123], v[158:161], v[202:205], v[120:123]
	v_mfma_f32_16x16x32_bf16 v[108:111], v[150:153], v[210:213], v[108:111]
	v_mfma_f32_16x16x32_bf16 v[104:107], v[158:161], v[210:213], v[104:107]
	v_mfma_f32_16x16x32_bf16 v[92:95], v[150:153], v[218:221], v[92:95]
	v_mfma_f32_16x16x32_bf16 v[88:91], v[158:161], v[218:221], v[88:91]
	v_mfma_f32_16x16x32_bf16 v[76:79], v[150:153], v[226:229], v[76:79]
	v_mfma_f32_16x16x32_bf16 v[72:75], v[158:161], v[226:229], v[72:75]
	s_setprio 0
	s_setprio 1
	v_mfma_f32_16x16x32_bf16 v[116:119], v[162:165], v[194:197], v[116:119]
	v_mfma_f32_16x16x32_bf16 v[112:115], v[186:189], v[194:197], v[112:115]
	v_mfma_f32_16x16x32_bf16 v[100:103], v[162:165], v[206:209], v[100:103]
	v_mfma_f32_16x16x32_bf16 v[96:99], v[186:189], v[206:209], v[96:99]
	v_mfma_f32_16x16x32_bf16 v[84:87], v[162:165], v[214:217], v[84:87]
	v_mfma_f32_16x16x32_bf16 v[80:83], v[186:189], v[214:217], v[80:83]
	v_mfma_f32_16x16x32_bf16 v[68:71], v[162:165], v[222:225], v[68:71]
	v_mfma_f32_16x16x32_bf16 v[64:67], v[186:189], v[222:225], v[64:67]
	v_mfma_f32_16x16x32_bf16 v[116:119], v[182:185], v[202:205], v[116:119]
	v_mfma_f32_16x16x32_bf16 v[112:115], v[190:193], v[202:205], v[112:115]
	v_mfma_f32_16x16x32_bf16 v[100:103], v[182:185], v[210:213], v[100:103]
	v_mfma_f32_16x16x32_bf16 v[96:99], v[190:193], v[210:213], v[96:99]
	v_mfma_f32_16x16x32_bf16 v[84:87], v[182:185], v[218:221], v[84:87]
	v_mfma_f32_16x16x32_bf16 v[80:83], v[190:193], v[218:221], v[80:83]
	v_mfma_f32_16x16x32_bf16 v[68:71], v[182:185], v[226:229], v[68:71]
	v_mfma_f32_16x16x32_bf16 v[64:67], v[190:193], v[226:229], v[64:67]
	s_setprio 0
	s_barrier
	s_add_i32 s35, s54, s9
	v_lshl_add_u64 v[198:199], s[38:39], 0, v[130:131]
	s_mov_b32 m0, s35
	ds_read_b128 v[194:197], v172 offset:16384
	ds_read_b128 v[202:205], v172 offset:17408
	ds_read_b128 v[206:209], v172 offset:18432
	ds_read_b128 v[210:213], v172 offset:19456
	ds_read_b128 v[214:217], v172 offset:20480
	ds_read_b128 v[218:221], v172 offset:21504
	ds_read_b128 v[222:225], v172 offset:22528
	ds_read_b128 v[226:229], v172 offset:23552
	global_load_lds_dwordx4 v[198:199], off
	s_add_i32 m0, s35, 0x2000
	s_add_u32 s58, s38, 0x40000
	v_lshl_add_u64 v[230:231], s[38:39], 0, v[134:135]
	s_addc_u32 s59, s39, 0
	s_add_i32 s35, s55, s9
	global_load_lds_dwordx4 v[230:231], off
	v_lshl_add_u64 v[232:233], s[58:59], 0, v[130:131]
	s_mov_b32 m0, s35
	v_lshl_add_u64 v[234:235], s[40:41], 0, v[132:133]
	global_load_lds_dwordx4 v[232:233], off
	v_lshl_add_u64 v[232:233], s[58:59], 0, v[134:135]
	s_add_i32 m0, s35, 0x2000
	s_nop 0
	global_load_lds_dwordx4 v[232:233], off
	v_lshl_add_u64 v[232:233], s[40:41], 0, v[128:129]
	s_mov_b32 m0, s13
	s_nop 0
	global_load_lds_dwordx4 v[232:233], off
	s_mov_b32 m0, s43
	s_nop 0
	global_load_lds_dwordx4 v[234:235], off
	s_waitcnt vmcnt(13)
	s_waitcnt lgkmcnt(0)
	s_barrier
	s_setprio 1
	s_waitcnt lgkmcnt(0)
	v_mfma_f32_16x16x32_bf16 v[60:63], v[146:149], v[194:197], v[60:63]
	v_mfma_f32_16x16x32_bf16 v[56:59], v[154:157], v[194:197], v[56:59]
	v_mfma_f32_16x16x32_bf16 v[44:47], v[146:149], v[206:209], v[44:47]
	v_mfma_f32_16x16x32_bf16 v[40:43], v[154:157], v[206:209], v[40:43]
	v_mfma_f32_16x16x32_bf16 v[28:31], v[146:149], v[214:217], v[28:31]
	v_mfma_f32_16x16x32_bf16 v[24:27], v[154:157], v[214:217], v[24:27]
	v_mfma_f32_16x16x32_bf16 v[12:15], v[146:149], v[222:225], v[12:15]
	v_mfma_f32_16x16x32_bf16 v[8:11], v[154:157], v[222:225], v[8:11]
	v_mfma_f32_16x16x32_bf16 v[60:63], v[150:153], v[202:205], v[60:63]
	v_mfma_f32_16x16x32_bf16 v[56:59], v[158:161], v[202:205], v[56:59]
	v_mfma_f32_16x16x32_bf16 v[44:47], v[150:153], v[210:213], v[44:47]
	v_mfma_f32_16x16x32_bf16 v[40:43], v[158:161], v[210:213], v[40:43]
	v_mfma_f32_16x16x32_bf16 v[28:31], v[150:153], v[218:221], v[28:31]
	v_mfma_f32_16x16x32_bf16 v[24:27], v[158:161], v[218:221], v[24:27]
	v_mfma_f32_16x16x32_bf16 v[12:15], v[150:153], v[226:229], v[12:15]
	v_mfma_f32_16x16x32_bf16 v[8:11], v[158:161], v[226:229], v[8:11]
	s_setprio 0
	s_setprio 1
	v_mfma_f32_16x16x32_bf16 v[52:55], v[162:165], v[194:197], v[52:55]
	v_mfma_f32_16x16x32_bf16 v[48:51], v[186:189], v[194:197], v[48:51]
	v_mfma_f32_16x16x32_bf16 v[36:39], v[162:165], v[206:209], v[36:39]
	v_mfma_f32_16x16x32_bf16 v[32:35], v[186:189], v[206:209], v[32:35]
	v_mfma_f32_16x16x32_bf16 v[20:23], v[162:165], v[214:217], v[20:23]
	v_mfma_f32_16x16x32_bf16 v[16:19], v[186:189], v[214:217], v[16:19]
	v_mfma_f32_16x16x32_bf16 v[4:7], v[162:165], v[222:225], v[4:7]
	v_mfma_f32_16x16x32_bf16 v[0:3], v[186:189], v[222:225], v[0:3]
	v_mfma_f32_16x16x32_bf16 v[52:55], v[182:185], v[202:205], v[52:55]
	v_mfma_f32_16x16x32_bf16 v[48:51], v[190:193], v[202:205], v[48:51]
	v_mfma_f32_16x16x32_bf16 v[36:39], v[182:185], v[210:213], v[36:39]
	v_mfma_f32_16x16x32_bf16 v[32:35], v[190:193], v[210:213], v[32:35]
	v_mfma_f32_16x16x32_bf16 v[20:23], v[182:185], v[218:221], v[20:23]
	v_mfma_f32_16x16x32_bf16 v[16:19], v[190:193], v[218:221], v[16:19]
	v_mfma_f32_16x16x32_bf16 v[4:7], v[182:185], v[226:229], v[4:7]
	v_mfma_f32_16x16x32_bf16 v[0:3], v[190:193], v[226:229], v[0:3]
	s_setprio 0
	s_barrier
	s_add_i32 s35, 0, 0x18000
	s_add_i32 s58, 0, 0x1c000
	v_add_u32_e32 v158, s35, v167
	v_add_u32_e32 v190, s58, v167
	ds_read_b128 v[146:149], v158
	ds_read_b128 v[150:153], v158 offset:1024
	ds_read_b128 v[154:157], v158 offset:2048
	ds_read_b128 v[158:161], v158 offset:3072
	ds_read_b128 v[162:165], v190
	ds_read_b128 v[182:185], v190 offset:1024
	ds_read_b128 v[186:189], v190 offset:2048
	ds_read_b128 v[190:193], v190 offset:3072
	s_add_u32 s40, s40, 0x40000
	s_addc_u32 s41, s41, 0
	s_mov_b32 m0, s45
	v_lshl_add_u64 v[236:237], s[40:41], 0, v[128:129]
	ds_read_b128 v[194:197], v172 offset:32768
	ds_read_b128 v[202:205], v172 offset:33792
	ds_read_b128 v[206:209], v172 offset:34816
	ds_read_b128 v[210:213], v172 offset:35840
	ds_read_b128 v[214:217], v172 offset:36864
	ds_read_b128 v[218:221], v172 offset:37888
	ds_read_b128 v[222:225], v172 offset:38912
	ds_read_b128 v[226:229], v172 offset:39936
	global_load_lds_dwordx4 v[236:237], off
	v_lshl_add_u64 v[236:237], s[40:41], 0, v[132:133]
	s_mov_b32 m0, s46
	s_nop 0
	global_load_lds_dwordx4 v[236:237], off
	s_waitcnt vmcnt(13)
	s_waitcnt lgkmcnt(0)
	s_barrier
	s_setprio 1
	s_waitcnt lgkmcnt(0)
	v_mfma_f32_16x16x32_bf16 v[124:127], v[146:149], v[194:197], v[124:127]
	v_mfma_f32_16x16x32_bf16 v[120:123], v[154:157], v[194:197], v[120:123]
	v_mfma_f32_16x16x32_bf16 v[108:111], v[146:149], v[206:209], v[108:111]
	v_mfma_f32_16x16x32_bf16 v[104:107], v[154:157], v[206:209], v[104:107]
	v_mfma_f32_16x16x32_bf16 v[92:95], v[146:149], v[214:217], v[92:95]
	v_mfma_f32_16x16x32_bf16 v[88:91], v[154:157], v[214:217], v[88:91]
	v_mfma_f32_16x16x32_bf16 v[76:79], v[146:149], v[222:225], v[76:79]
	v_mfma_f32_16x16x32_bf16 v[72:75], v[154:157], v[222:225], v[72:75]
	v_mfma_f32_16x16x32_bf16 v[124:127], v[150:153], v[202:205], v[124:127]
	v_mfma_f32_16x16x32_bf16 v[120:123], v[158:161], v[202:205], v[120:123]
	v_mfma_f32_16x16x32_bf16 v[108:111], v[150:153], v[210:213], v[108:111]
	v_mfma_f32_16x16x32_bf16 v[104:107], v[158:161], v[210:213], v[104:107]
	v_mfma_f32_16x16x32_bf16 v[92:95], v[150:153], v[218:221], v[92:95]
	v_mfma_f32_16x16x32_bf16 v[88:91], v[158:161], v[218:221], v[88:91]
	v_mfma_f32_16x16x32_bf16 v[76:79], v[150:153], v[226:229], v[76:79]
	v_mfma_f32_16x16x32_bf16 v[72:75], v[158:161], v[226:229], v[72:75]
	s_setprio 0
	s_setprio 1
	v_mfma_f32_16x16x32_bf16 v[116:119], v[162:165], v[194:197], v[116:119]
	v_mfma_f32_16x16x32_bf16 v[112:115], v[186:189], v[194:197], v[112:115]
	v_mfma_f32_16x16x32_bf16 v[100:103], v[162:165], v[206:209], v[100:103]
	v_mfma_f32_16x16x32_bf16 v[96:99], v[186:189], v[206:209], v[96:99]
	v_mfma_f32_16x16x32_bf16 v[84:87], v[162:165], v[214:217], v[84:87]
	v_mfma_f32_16x16x32_bf16 v[80:83], v[186:189], v[214:217], v[80:83]
	v_mfma_f32_16x16x32_bf16 v[68:71], v[162:165], v[222:225], v[68:71]
	v_mfma_f32_16x16x32_bf16 v[64:67], v[186:189], v[222:225], v[64:67]
	v_mfma_f32_16x16x32_bf16 v[116:119], v[182:185], v[202:205], v[116:119]
	v_mfma_f32_16x16x32_bf16 v[112:115], v[190:193], v[202:205], v[112:115]
	v_mfma_f32_16x16x32_bf16 v[100:103], v[182:185], v[210:213], v[100:103]
	v_mfma_f32_16x16x32_bf16 v[96:99], v[190:193], v[210:213], v[96:99]
	v_mfma_f32_16x16x32_bf16 v[84:87], v[182:185], v[218:221], v[84:87]
	v_mfma_f32_16x16x32_bf16 v[80:83], v[190:193], v[218:221], v[80:83]
	v_mfma_f32_16x16x32_bf16 v[68:71], v[182:185], v[226:229], v[68:71]
	v_mfma_f32_16x16x32_bf16 v[64:67], v[190:193], v[226:229], v[64:67]
	s_setprio 0
	s_barrier
	s_add_i32 s35, s35, s9
	v_lshl_add_u64 v[198:199], v[198:199], 0, s[10:11]
	s_mov_b32 m0, s35
	ds_read_b128 v[194:197], v172 offset:49152
	ds_read_b128 v[202:205], v172 offset:50176
	ds_read_b128 v[206:209], v172 offset:51200
	ds_read_b128 v[210:213], v172 offset:52224
	ds_read_b128 v[214:217], v172 offset:53248
	ds_read_b128 v[218:221], v172 offset:54272
	ds_read_b128 v[222:225], v172 offset:55296
	ds_read_b128 v[226:229], v172 offset:56320
	global_load_lds_dwordx4 v[198:199], off
	s_add_i32 m0, s35, 0x2000
	s_add_u32 s38, s38, 0x40080
	v_lshl_add_u64 v[198:199], v[230:231], 0, s[10:11]
	s_addc_u32 s39, s39, 0
	s_add_i32 s35, s58, s9
	global_load_lds_dwordx4 v[198:199], off
	v_lshl_add_u64 v[198:199], s[38:39], 0, v[130:131]
	s_mov_b32 m0, s35
	s_nop 0
	global_load_lds_dwordx4 v[198:199], off
	v_lshl_add_u64 v[198:199], s[38:39], 0, v[134:135]
	s_add_i32 m0, s35, 0x2000
	s_nop 0
	global_load_lds_dwordx4 v[198:199], off
	v_lshl_add_u64 v[198:199], v[232:233], 0, s[10:11]
	s_mov_b32 m0, s51
	s_nop 0
	global_load_lds_dwordx4 v[198:199], off
	v_lshl_add_u64 v[198:199], v[234:235], 0, s[10:11]
	s_mov_b32 m0, s52
	s_nop 0
	global_load_lds_dwordx4 v[198:199], off
	s_waitcnt vmcnt(13)
	s_waitcnt lgkmcnt(0)
	s_barrier
	s_setprio 1
	s_waitcnt lgkmcnt(0)
	v_mfma_f32_16x16x32_bf16 v[60:63], v[146:149], v[194:197], v[60:63]
	v_mfma_f32_16x16x32_bf16 v[56:59], v[154:157], v[194:197], v[56:59]
	v_mfma_f32_16x16x32_bf16 v[44:47], v[146:149], v[206:209], v[44:47]
	v_mfma_f32_16x16x32_bf16 v[40:43], v[154:157], v[206:209], v[40:43]
	v_mfma_f32_16x16x32_bf16 v[28:31], v[146:149], v[214:217], v[28:31]
	v_mfma_f32_16x16x32_bf16 v[24:27], v[154:157], v[214:217], v[24:27]
	v_mfma_f32_16x16x32_bf16 v[12:15], v[146:149], v[222:225], v[12:15]
	v_mfma_f32_16x16x32_bf16 v[8:11], v[154:157], v[222:225], v[8:11]
	v_mfma_f32_16x16x32_bf16 v[60:63], v[150:153], v[202:205], v[60:63]
	v_mfma_f32_16x16x32_bf16 v[56:59], v[158:161], v[202:205], v[56:59]
	v_mfma_f32_16x16x32_bf16 v[44:47], v[150:153], v[210:213], v[44:47]
	v_mfma_f32_16x16x32_bf16 v[40:43], v[158:161], v[210:213], v[40:43]
	v_mfma_f32_16x16x32_bf16 v[28:31], v[150:153], v[218:221], v[28:31]
	v_mfma_f32_16x16x32_bf16 v[24:27], v[158:161], v[218:221], v[24:27]
	v_mfma_f32_16x16x32_bf16 v[12:15], v[150:153], v[226:229], v[12:15]
	v_mfma_f32_16x16x32_bf16 v[8:11], v[158:161], v[226:229], v[8:11]
	s_setprio 0
	s_setprio 1
	v_mfma_f32_16x16x32_bf16 v[52:55], v[162:165], v[194:197], v[52:55]
	v_mfma_f32_16x16x32_bf16 v[48:51], v[186:189], v[194:197], v[48:51]
	v_mfma_f32_16x16x32_bf16 v[36:39], v[162:165], v[206:209], v[36:39]
	v_mfma_f32_16x16x32_bf16 v[32:35], v[186:189], v[206:209], v[32:35]
	v_mfma_f32_16x16x32_bf16 v[20:23], v[162:165], v[214:217], v[20:23]
	v_mfma_f32_16x16x32_bf16 v[16:19], v[186:189], v[214:217], v[16:19]
	v_mfma_f32_16x16x32_bf16 v[4:7], v[162:165], v[222:225], v[4:7]
	v_mfma_f32_16x16x32_bf16 v[0:3], v[186:189], v[222:225], v[0:3]
	v_mfma_f32_16x16x32_bf16 v[52:55], v[182:185], v[202:205], v[52:55]
	v_mfma_f32_16x16x32_bf16 v[48:51], v[190:193], v[202:205], v[48:51]
	v_mfma_f32_16x16x32_bf16 v[36:39], v[182:185], v[210:213], v[36:39]
	v_mfma_f32_16x16x32_bf16 v[32:35], v[190:193], v[210:213], v[32:35]
	v_mfma_f32_16x16x32_bf16 v[20:23], v[182:185], v[218:221], v[20:23]
	v_mfma_f32_16x16x32_bf16 v[16:19], v[190:193], v[218:221], v[16:19]
	v_mfma_f32_16x16x32_bf16 v[4:7], v[182:185], v[226:229], v[4:7]
	v_mfma_f32_16x16x32_bf16 v[0:3], v[190:193], v[226:229], v[0:3]
	s_setprio 0
	s_barrier
	s_add_i32 s33, s33, 2
	s_add_u32 s36, s36, 0x100
	s_addc_u32 s37, s37, 0
	s_add_u32 s21, s21, 0x100
	s_addc_u32 s23, s23, 0
	s_and_b64 vcc, exec, s[14:15]
	s_cbranch_vccz .LBB0_517
	s_barrier
.LBB0_517:
	s_mov_b32 s35, s34
	v_lshl_add_u32 v227, s34, 8, v166
	v_lshlrev_b32_e32 v227, 6, v227
	v_add_u32_e32 v227, 0x2000, v227
	v_add_co_u32_e32 v164, vcc, v136, v227
	s_nop 1
	v_addc_co_u32_e32 v165, vcc, 0, v137, vcc
	global_load_dwordx4 v[182:185], v[164:165], off
	global_load_dwordx4 v[186:189], v[164:165], off offset:1024
	global_load_dwordx4 v[190:193], v[164:165], off offset:2048
	global_load_dwordx4 v[194:197], v[164:165], off offset:3072
	v_xor_b32_e32 v198, 16, v173
	v_xor_b32_e32 v199, 32, v173
	v_lshlrev_b32_e32 v198, 2, v198
	v_lshlrev_b32_e32 v199, 2, v199
	s_waitcnt vmcnt(12)
	v_add_f32_e32 v238, v238, v239
	v_add_f32_e32 v240, v240, v241
	v_add_f32_e32 v218, v238, v240
	v_add_f32_e32 v242, v242, v243
	v_add_f32_e32 v244, v244, v245
	v_add_f32_e32 v219, v242, v244
	v_add_f32_e32 v250, v250, v251
	v_add_f32_e32 v252, v252, v253
	v_add_f32_e32 v220, v250, v252
	v_add_f32_e32 v246, v246, v247
	v_add_f32_e32 v254, v254, v255
	v_add_f32_e32 v221, v246, v254
	v_max3_f32 v202, v124, v125, v126
	v_max3_f32 v203, v127, v120, v121
	v_max3_f32 v202, v202, v122, v123
	v_max3_f32 v203, v203, v116, v117
	v_max3_f32 v202, v202, v118, v119
	v_max3_f32 v203, v203, v112, v113
	v_max3_f32 v202, v202, v114, v115
	v_max_f32_e32 v202, v202, v203
	v_max3_f32 v204, v108, v109, v110
	v_max3_f32 v205, v111, v104, v105
	v_max3_f32 v204, v204, v106, v107
	v_max3_f32 v205, v205, v100, v101
	v_max3_f32 v204, v204, v102, v103
	v_max3_f32 v205, v205, v96, v97
	v_max3_f32 v204, v204, v98, v99
	v_max_f32_e32 v204, v204, v205
	v_max3_f32 v206, v92, v93, v94
	v_max3_f32 v207, v95, v88, v89
	v_max3_f32 v206, v206, v90, v91
	v_max3_f32 v207, v207, v84, v85
	v_max3_f32 v206, v206, v86, v87
	v_max3_f32 v207, v207, v80, v81
	v_max3_f32 v206, v206, v82, v83
	v_max_f32_e32 v206, v206, v207
	v_max3_f32 v208, v76, v77, v78
	v_max3_f32 v209, v79, v72, v73
	v_max3_f32 v208, v208, v74, v75
	v_max3_f32 v209, v209, v68, v69
	v_max3_f32 v208, v208, v70, v71
	v_max3_f32 v209, v209, v64, v65
	v_max3_f32 v208, v208, v66, v67
	v_max_f32_e32 v208, v208, v209
	v_max3_f32 v210, v60, v61, v62
	v_max3_f32 v211, v63, v56, v57
	v_max3_f32 v210, v210, v58, v59
	v_max3_f32 v211, v211, v52, v53
	v_max3_f32 v210, v210, v54, v55
	v_max3_f32 v211, v211, v48, v49
	v_max3_f32 v210, v210, v50, v51
	v_max_f32_e32 v210, v210, v211
	v_max3_f32 v212, v44, v45, v46
	v_max3_f32 v213, v47, v40, v41
	v_max3_f32 v212, v212, v42, v43
	v_max3_f32 v213, v213, v36, v37
	v_max3_f32 v212, v212, v38, v39
	v_max3_f32 v213, v213, v32, v33
	v_max3_f32 v212, v212, v34, v35
	v_max_f32_e32 v212, v212, v213
	v_max3_f32 v214, v28, v29, v30
	v_max3_f32 v215, v31, v24, v25
	v_max3_f32 v214, v214, v26, v27
	v_max3_f32 v215, v215, v20, v21
	v_max3_f32 v214, v214, v22, v23
	v_max3_f32 v215, v215, v16, v17
	v_max3_f32 v214, v214, v18, v19
	v_max_f32_e32 v214, v214, v215
	v_max3_f32 v216, v12, v13, v14
	v_max3_f32 v217, v15, v8, v9
	v_max3_f32 v216, v216, v10, v11
	v_max3_f32 v217, v217, v4, v5
	v_max3_f32 v216, v216, v6, v7
	v_max3_f32 v217, v217, v0, v1
	v_max3_f32 v216, v216, v2, v3
	v_max_f32_e32 v216, v216, v217
	ds_bpermute_b32 v249, v198, v202
	ds_bpermute_b32 v250, v198, v204
	ds_bpermute_b32 v251, v198, v206
	ds_bpermute_b32 v226, v198, v208
	ds_bpermute_b32 v162, v198, v210
	ds_bpermute_b32 v163, v198, v212
	ds_bpermute_b32 v164, v198, v214
	ds_bpermute_b32 v165, v198, v216
	s_waitcnt lgkmcnt(7)
	v_max_f32_e32 v202, v202, v249
	s_waitcnt lgkmcnt(6)
	v_max_f32_e32 v204, v204, v250
	s_waitcnt lgkmcnt(5)
	v_max_f32_e32 v206, v206, v251
	s_waitcnt lgkmcnt(4)
	v_max_f32_e32 v208, v208, v226
	s_waitcnt lgkmcnt(3)
	v_max_f32_e32 v210, v210, v162
	s_waitcnt lgkmcnt(2)
	v_max_f32_e32 v212, v212, v163
	s_waitcnt lgkmcnt(1)
	v_max_f32_e32 v214, v214, v164
	s_waitcnt lgkmcnt(0)
	v_max_f32_e32 v216, v216, v165
	ds_bpermute_b32 v249, v199, v202
	ds_bpermute_b32 v250, v199, v204
	ds_bpermute_b32 v251, v199, v206
	ds_bpermute_b32 v226, v199, v208
	ds_bpermute_b32 v162, v199, v210
	ds_bpermute_b32 v163, v199, v212
	ds_bpermute_b32 v164, v199, v214
	ds_bpermute_b32 v165, v199, v216
	s_waitcnt lgkmcnt(7)
	v_max_f32_e32 v202, v202, v249
	s_waitcnt lgkmcnt(6)
	v_max_f32_e32 v204, v204, v250
	s_waitcnt lgkmcnt(5)
	v_max_f32_e32 v206, v206, v251
	s_waitcnt lgkmcnt(4)
	v_max_f32_e32 v208, v208, v226
	s_waitcnt lgkmcnt(3)
	v_max_f32_e32 v210, v210, v162
	s_waitcnt lgkmcnt(2)
	v_max_f32_e32 v212, v212, v163
	s_waitcnt lgkmcnt(1)
	v_max_f32_e32 v214, v214, v164
	s_waitcnt lgkmcnt(0)
	v_max_f32_e32 v216, v216, v165
	v_lshl_add_u32 v229, s35, 8, v166
	v_lshlrev_b32_e32 v229, 11, v229
	v_lshl_or_b32 v228, s57, 9, v169
	v_add_u32_e32 v229, v229, v228
	v_add_u32_e32 v201, s53, v168
	ds_bpermute_b32 v249, v198, v218
	ds_bpermute_b32 v250, v198, v219
	ds_bpermute_b32 v251, v198, v220
	ds_bpermute_b32 v226, v198, v221
	s_waitcnt lgkmcnt(3)
	v_add_f32_e32 v218, v218, v249
	s_waitcnt lgkmcnt(2)
	v_add_f32_e32 v219, v219, v250
	s_waitcnt lgkmcnt(1)
	v_add_f32_e32 v220, v220, v251
	s_waitcnt lgkmcnt(0)
	v_add_f32_e32 v221, v221, v226
	ds_bpermute_b32 v249, v199, v218
	ds_bpermute_b32 v250, v199, v219
	ds_bpermute_b32 v251, v199, v220
	ds_bpermute_b32 v226, v199, v221
	s_waitcnt lgkmcnt(3)
	v_add_f32_e32 v218, v218, v249
	s_waitcnt lgkmcnt(2)
	v_add_f32_e32 v219, v219, v250
	s_waitcnt lgkmcnt(1)
	v_add_f32_e32 v220, v220, v251
	s_waitcnt lgkmcnt(0)
	v_add_f32_e32 v221, v221, v226
	v_fmamk_f32 v218, v218, 0x3a800000, v174
	v_fmamk_f32 v219, v219, 0x3a800000, v174
	v_fmamk_f32 v220, v220, 0x3a800000, v174
	v_fmamk_f32 v221, v221, 0x3a800000, v174
	v_rsq_f32_e32 v218, v218
	v_rsq_f32_e32 v219, v219
	v_rsq_f32_e32 v220, v220
	v_rsq_f32_e32 v221, v221
	s_mov_b32 s34, 0x3db8aa3b
	v_mul_f32_e32 v218, s34, v218
	v_mul_f32_e32 v219, s34, v219
	v_mul_f32_e32 v220, s34, v220
	v_mul_f32_e32 v221, s34, v221
	v_mul_f32_e32 v202, v202, v218
	v_mul_f32_e32 v204, v204, v219
	v_mul_f32_e32 v206, v206, v220
	v_mul_f32_e32 v208, v208, v221
	v_pk_fma_f32 v[124:125], v[124:125], v[218:219], v[202:203] op_sel:[0,0,0] op_sel_hi:[1,0,0] neg_lo:[0,0,1] neg_hi:[0,0,1]
	v_pk_fma_f32 v[126:127], v[126:127], v[218:219], v[202:203] op_sel:[0,0,0] op_sel_hi:[1,0,0] neg_lo:[0,0,1] neg_hi:[0,0,1]
	v_pk_fma_f32 v[120:121], v[120:121], v[218:219], v[202:203] op_sel:[0,0,0] op_sel_hi:[1,0,0] neg_lo:[0,0,1] neg_hi:[0,0,1]
	v_pk_fma_f32 v[122:123], v[122:123], v[218:219], v[202:203] op_sel:[0,0,0] op_sel_hi:[1,0,0] neg_lo:[0,0,1] neg_hi:[0,0,1]
	v_pk_fma_f32 v[116:117], v[116:117], v[218:219], v[202:203] op_sel:[0,0,0] op_sel_hi:[1,0,0] neg_lo:[0,0,1] neg_hi:[0,0,1]
	v_pk_fma_f32 v[118:119], v[118:119], v[218:219], v[202:203] op_sel:[0,0,0] op_sel_hi:[1,0,0] neg_lo:[0,0,1] neg_hi:[0,0,1]
	v_pk_fma_f32 v[112:113], v[112:113], v[218:219], v[202:203] op_sel:[0,0,0] op_sel_hi:[1,0,0] neg_lo:[0,0,1] neg_hi:[0,0,1]
	v_pk_fma_f32 v[114:115], v[114:115], v[218:219], v[202:203] op_sel:[0,0,0] op_sel_hi:[1,0,0] neg_lo:[0,0,1] neg_hi:[0,0,1]
	v_exp_f32_e32 v124, v124
	v_exp_f32_e32 v125, v125
	v_exp_f32_e32 v126, v126
	v_exp_f32_e32 v127, v127
	v_exp_f32_e32 v120, v120
	v_exp_f32_e32 v121, v121
	v_exp_f32_e32 v122, v122
	v_exp_f32_e32 v123, v123
	v_exp_f32_e32 v116, v116
	v_exp_f32_e32 v117, v117
	v_exp_f32_e32 v118, v118
	v_exp_f32_e32 v119, v119
	v_exp_f32_e32 v112, v112
	v_exp_f32_e32 v113, v113
	v_exp_f32_e32 v114, v114
	v_exp_f32_e32 v115, v115
	v_pk_add_f32 v[162:163], v[124:125], v[126:127]
	v_pk_add_f32 v[164:165], v[120:121], v[122:123]
	v_pk_add_f32 v[252:253], v[116:117], v[118:119]
	v_pk_add_f32 v[254:255], v[112:113], v[114:115]
	v_pk_add_f32 v[162:163], v[162:163], v[164:165]
	v_pk_add_f32 v[252:253], v[252:253], v[254:255]
	v_pk_add_f32 v[162:163], v[162:163], v[252:253]
	v_add_f32_e32 v203, v162, v163
	v_pk_fma_f32 v[108:109], v[108:109], v[218:219], v[204:205] op_sel:[0,1,0] op_sel_hi:[1,1,0] neg_lo:[0,0,1] neg_hi:[0,0,1]
	v_pk_fma_f32 v[110:111], v[110:111], v[218:219], v[204:205] op_sel:[0,1,0] op_sel_hi:[1,1,0] neg_lo:[0,0,1] neg_hi:[0,0,1]
	v_pk_fma_f32 v[104:105], v[104:105], v[218:219], v[204:205] op_sel:[0,1,0] op_sel_hi:[1,1,0] neg_lo:[0,0,1] neg_hi:[0,0,1]
	v_pk_fma_f32 v[106:107], v[106:107], v[218:219], v[204:205] op_sel:[0,1,0] op_sel_hi:[1,1,0] neg_lo:[0,0,1] neg_hi:[0,0,1]
	v_pk_fma_f32 v[100:101], v[100:101], v[218:219], v[204:205] op_sel:[0,1,0] op_sel_hi:[1,1,0] neg_lo:[0,0,1] neg_hi:[0,0,1]
	v_pk_fma_f32 v[102:103], v[102:103], v[218:219], v[204:205] op_sel:[0,1,0] op_sel_hi:[1,1,0] neg_lo:[0,0,1] neg_hi:[0,0,1]
	v_pk_fma_f32 v[96:97], v[96:97], v[218:219], v[204:205] op_sel:[0,1,0] op_sel_hi:[1,1,0] neg_lo:[0,0,1] neg_hi:[0,0,1]
	v_pk_fma_f32 v[98:99], v[98:99], v[218:219], v[204:205] op_sel:[0,1,0] op_sel_hi:[1,1,0] neg_lo:[0,0,1] neg_hi:[0,0,1]
	v_exp_f32_e32 v108, v108
	v_exp_f32_e32 v109, v109
	v_exp_f32_e32 v110, v110
	v_exp_f32_e32 v111, v111
	v_exp_f32_e32 v104, v104
	v_exp_f32_e32 v105, v105
	v_exp_f32_e32 v106, v106
	v_exp_f32_e32 v107, v107
	v_exp_f32_e32 v100, v100
	v_exp_f32_e32 v101, v101
	v_exp_f32_e32 v102, v102
	v_exp_f32_e32 v103, v103
	v_exp_f32_e32 v96, v96
	v_exp_f32_e32 v97, v97
	v_exp_f32_e32 v98, v98
	v_exp_f32_e32 v99, v99
	v_pk_add_f32 v[162:163], v[108:109], v[110:111]
	v_pk_add_f32 v[164:165], v[104:105], v[106:107]
	v_pk_add_f32 v[252:253], v[100:101], v[102:103]
	v_pk_add_f32 v[254:255], v[96:97], v[98:99]
	v_pk_add_f32 v[162:163], v[162:163], v[164:165]
	v_pk_add_f32 v[252:253], v[252:253], v[254:255]
	v_pk_add_f32 v[162:163], v[162:163], v[252:253]
	v_add_f32_e32 v205, v162, v163
	ds_bpermute_b32 v249, v198, v203
	ds_bpermute_b32 v250, v198, v205
	v_pk_fma_f32 v[92:93], v[92:93], v[220:221], v[206:207] op_sel:[0,0,0] op_sel_hi:[1,0,0] neg_lo:[0,0,1] neg_hi:[0,0,1]
	v_pk_fma_f32 v[94:95], v[94:95], v[220:221], v[206:207] op_sel:[0,0,0] op_sel_hi:[1,0,0] neg_lo:[0,0,1] neg_hi:[0,0,1]
	v_pk_fma_f32 v[88:89], v[88:89], v[220:221], v[206:207] op_sel:[0,0,0] op_sel_hi:[1,0,0] neg_lo:[0,0,1] neg_hi:[0,0,1]
	v_pk_fma_f32 v[90:91], v[90:91], v[220:221], v[206:207] op_sel:[0,0,0] op_sel_hi:[1,0,0] neg_lo:[0,0,1] neg_hi:[0,0,1]
	v_pk_fma_f32 v[84:85], v[84:85], v[220:221], v[206:207] op_sel:[0,0,0] op_sel_hi:[1,0,0] neg_lo:[0,0,1] neg_hi:[0,0,1]
	v_pk_fma_f32 v[86:87], v[86:87], v[220:221], v[206:207] op_sel:[0,0,0] op_sel_hi:[1,0,0] neg_lo:[0,0,1] neg_hi:[0,0,1]
	v_pk_fma_f32 v[80:81], v[80:81], v[220:221], v[206:207] op_sel:[0,0,0] op_sel_hi:[1,0,0] neg_lo:[0,0,1] neg_hi:[0,0,1]
	v_pk_fma_f32 v[82:83], v[82:83], v[220:221], v[206:207] op_sel:[0,0,0] op_sel_hi:[1,0,0] neg_lo:[0,0,1] neg_hi:[0,0,1]
	v_exp_f32_e32 v92, v92
	v_exp_f32_e32 v93, v93
	v_exp_f32_e32 v94, v94
	v_exp_f32_e32 v95, v95
	v_exp_f32_e32 v88, v88
	v_exp_f32_e32 v89, v89
	v_exp_f32_e32 v90, v90
	v_exp_f32_e32 v91, v91
	s_waitcnt lgkmcnt(1)
	v_add_f32_e32 v203, v203, v249
	s_waitcnt lgkmcnt(0)
	v_add_f32_e32 v205, v205, v250
	ds_bpermute_b32 v249, v199, v203
	ds_bpermute_b32 v250, v199, v205
	v_exp_f32_e32 v84, v84
	v_exp_f32_e32 v85, v85
	v_exp_f32_e32 v86, v86
	v_exp_f32_e32 v87, v87
	v_exp_f32_e32 v80, v80
	v_exp_f32_e32 v81, v81
	v_exp_f32_e32 v82, v82
	v_exp_f32_e32 v83, v83
	v_pk_add_f32 v[162:163], v[92:93], v[94:95]
	v_pk_add_f32 v[164:165], v[88:89], v[90:91]
	v_pk_add_f32 v[252:253], v[84:85], v[86:87]
	v_pk_add_f32 v[254:255], v[80:81], v[82:83]
	v_pk_add_f32 v[162:163], v[162:163], v[164:165]
	v_pk_add_f32 v[252:253], v[252:253], v[254:255]
	v_pk_add_f32 v[162:163], v[162:163], v[252:253]
	v_add_f32_e32 v207, v162, v163
	s_waitcnt lgkmcnt(1)
	v_add_f32_e32 v203, v203, v249
	s_waitcnt lgkmcnt(0)
	v_add_f32_e32 v205, v205, v250
	s_mov_b64 vcc, exec
	s_and_b64 exec, exec, s[0:1]
	ds_write_b64 v201, v[202:203]
	ds_write_b64 v175, v[204:205]
	s_mov_b64 exec, vcc
	v_pk_fma_f32 v[76:77], v[76:77], v[220:221], v[208:209] op_sel:[0,1,0] op_sel_hi:[1,1,0] neg_lo:[0,0,1] neg_hi:[0,0,1]
	v_pk_fma_f32 v[78:79], v[78:79], v[220:221], v[208:209] op_sel:[0,1,0] op_sel_hi:[1,1,0] neg_lo:[0,0,1] neg_hi:[0,0,1]
	v_pk_fma_f32 v[72:73], v[72:73], v[220:221], v[208:209] op_sel:[0,1,0] op_sel_hi:[1,1,0] neg_lo:[0,0,1] neg_hi:[0,0,1]
	v_pk_fma_f32 v[74:75], v[74:75], v[220:221], v[208:209] op_sel:[0,1,0] op_sel_hi:[1,1,0] neg_lo:[0,0,1] neg_hi:[0,0,1]
	v_pk_fma_f32 v[68:69], v[68:69], v[220:221], v[208:209] op_sel:[0,1,0] op_sel_hi:[1,1,0] neg_lo:[0,0,1] neg_hi:[0,0,1]
	v_pk_fma_f32 v[70:71], v[70:71], v[220:221], v[208:209] op_sel:[0,1,0] op_sel_hi:[1,1,0] neg_lo:[0,0,1] neg_hi:[0,0,1]
	v_pk_fma_f32 v[64:65], v[64:65], v[220:221], v[208:209] op_sel:[0,1,0] op_sel_hi:[1,1,0] neg_lo:[0,0,1] neg_hi:[0,0,1]
	v_pk_fma_f32 v[66:67], v[66:67], v[220:221], v[208:209] op_sel:[0,1,0] op_sel_hi:[1,1,0] neg_lo:[0,0,1] neg_hi:[0,0,1]
	v_exp_f32_e32 v76, v76
	v_exp_f32_e32 v77, v77
	v_exp_f32_e32 v78, v78
	v_exp_f32_e32 v79, v79
	v_exp_f32_e32 v72, v72
	v_exp_f32_e32 v73, v73
	v_exp_f32_e32 v74, v74
	v_exp_f32_e32 v75, v75
	s_waitcnt lgkmcnt(0)
	s_barrier
	ds_read_b128 v[146:149], v168
	ds_read_b128 v[150:153], v168 offset:16
	ds_read_b128 v[154:157], v168 offset:512
	ds_read_b128 v[158:161], v168 offset:528
	v_exp_f32_e32 v68, v68
	v_exp_f32_e32 v69, v69
	v_exp_f32_e32 v70, v70
	v_exp_f32_e32 v71, v71
	v_exp_f32_e32 v64, v64
	v_exp_f32_e32 v65, v65
	v_exp_f32_e32 v66, v66
	v_exp_f32_e32 v67, v67
	v_pk_add_f32 v[162:163], v[76:77], v[78:79]
	v_pk_add_f32 v[164:165], v[72:73], v[74:75]
	v_pk_add_f32 v[252:253], v[68:69], v[70:71]
	v_pk_add_f32 v[254:255], v[64:65], v[66:67]
	v_pk_add_f32 v[162:163], v[162:163], v[164:165]
	v_pk_add_f32 v[252:253], v[252:253], v[254:255]
	v_pk_add_f32 v[162:163], v[162:163], v[252:253]
	v_add_f32_e32 v209, v162, v163
	s_waitcnt lgkmcnt(2)
	v_max3_f32 v227, v146, v148, v150
	v_max_f32_e32 v227, v227, v152
	v_sub_f32_e32 v146, v146, v227
	v_sub_f32_e32 v148, v148, v227
	v_sub_f32_e32 v150, v150, v227
	v_sub_f32_e32 v152, v152, v227
	v_sub_f32_e32 v202, v202, v227
	v_exp_f32_e32 v146, v146
	v_exp_f32_e32 v148, v148
	v_exp_f32_e32 v150, v150
	v_exp_f32_e32 v152, v152
	v_exp_f32_e32 v202, v202
	v_mul_f32_e32 v228, v147, v146
	v_mul_f32_e32 v226, v151, v150
	v_fmac_f32_e32 v228, v149, v148
	v_fmac_f32_e32 v226, v153, v152
	v_add_f32_e32 v228, v228, v226
	v_rcp_f32_e32 v228, v228
	s_nop 0
	v_mul_f32_e32 v202, v202, v228
	s_mov_b32 s34, 0x0
	v_pk_mul_f32 v[124:125], v[124:125], v[202:203] op_sel:[0,0] op_sel_hi:[1,0]
	v_pk_mul_f32 v[126:127], v[126:127], v[202:203] op_sel:[0,0] op_sel_hi:[1,0]
	v_pk_mul_f32 v[120:121], v[120:121], v[202:203] op_sel:[0,0] op_sel_hi:[1,0]
	v_pk_mul_f32 v[122:123], v[122:123], v[202:203] op_sel:[0,0] op_sel_hi:[1,0]
	v_cvt_pk_bf16_f32 v124, v124, v125
	v_cvt_pk_bf16_f32 v125, v126, v127
	v_cvt_pk_bf16_f32 v126, v120, v121
	v_cvt_pk_bf16_f32 v127, v122, v123
	buffer_store_dwordx4 v[124:127], v229, s[16:19], s34 offen sc1
	v_pk_mul_f32 v[116:117], v[116:117], v[202:203] op_sel:[0,0] op_sel_hi:[1,0]
	v_pk_mul_f32 v[118:119], v[118:119], v[202:203] op_sel:[0,0] op_sel_hi:[1,0]
	v_pk_mul_f32 v[112:113], v[112:113], v[202:203] op_sel:[0,0] op_sel_hi:[1,0]
	v_pk_mul_f32 v[114:115], v[114:115], v[202:203] op_sel:[0,0] op_sel_hi:[1,0]
	v_cvt_pk_bf16_f32 v116, v116, v117
	v_cvt_pk_bf16_f32 v117, v118, v119
	v_cvt_pk_bf16_f32 v118, v112, v113
	v_cvt_pk_bf16_f32 v119, v114, v115
	buffer_store_dwordx4 v[116:119], v229, s[16:19], s34 offen offset:256 sc1
	s_waitcnt lgkmcnt(0)
	v_max3_f32 v227, v154, v156, v158
	v_max_f32_e32 v227, v227, v160
	v_sub_f32_e32 v154, v154, v227
	v_sub_f32_e32 v156, v156, v227
	v_sub_f32_e32 v158, v158, v227
	v_sub_f32_e32 v160, v160, v227
	v_sub_f32_e32 v204, v204, v227
	v_exp_f32_e32 v154, v154
	v_exp_f32_e32 v156, v156
	v_exp_f32_e32 v158, v158
	v_exp_f32_e32 v160, v160
	v_exp_f32_e32 v204, v204
	v_mul_f32_e32 v228, v155, v154
	v_mul_f32_e32 v226, v159, v158
	v_fmac_f32_e32 v228, v157, v156
	v_fmac_f32_e32 v226, v161, v160
	v_add_f32_e32 v228, v228, v226
	v_rcp_f32_e32 v228, v228
	s_nop 0
	v_mul_f32_e32 v204, v204, v228
	s_mov_b32 s34, 0x8000
	v_pk_mul_f32 v[108:109], v[108:109], v[204:205] op_sel:[0,0] op_sel_hi:[1,0]
	v_pk_mul_f32 v[110:111], v[110:111], v[204:205] op_sel:[0,0] op_sel_hi:[1,0]
	v_pk_mul_f32 v[104:105], v[104:105], v[204:205] op_sel:[0,0] op_sel_hi:[1,0]
	v_pk_mul_f32 v[106:107], v[106:107], v[204:205] op_sel:[0,0] op_sel_hi:[1,0]
	v_cvt_pk_bf16_f32 v108, v108, v109
	v_cvt_pk_bf16_f32 v109, v110, v111
	v_cvt_pk_bf16_f32 v110, v104, v105
	v_cvt_pk_bf16_f32 v111, v106, v107
	buffer_store_dwordx4 v[108:111], v229, s[16:19], s34 offen sc1
	v_pk_mul_f32 v[100:101], v[100:101], v[204:205] op_sel:[0,0] op_sel_hi:[1,0]
	v_pk_mul_f32 v[102:103], v[102:103], v[204:205] op_sel:[0,0] op_sel_hi:[1,0]
	v_pk_mul_f32 v[96:97], v[96:97], v[204:205] op_sel:[0,0] op_sel_hi:[1,0]
	v_pk_mul_f32 v[98:99], v[98:99], v[204:205] op_sel:[0,0] op_sel_hi:[1,0]
	v_cvt_pk_bf16_f32 v100, v100, v101
	v_cvt_pk_bf16_f32 v101, v102, v103
	v_cvt_pk_bf16_f32 v102, v96, v97
	v_cvt_pk_bf16_f32 v103, v98, v99
	buffer_store_dwordx4 v[100:103], v229, s[16:19], s34 offen offset:256 sc1
	s_waitcnt vmcnt(7)
	v_add_f32_e32 v182, v182, v183
	v_add_f32_e32 v184, v184, v185
	v_add_f32_e32 v222, v182, v184
	s_waitcnt vmcnt(6)
	v_add_f32_e32 v186, v186, v187
	v_add_f32_e32 v188, v188, v189
	v_add_f32_e32 v223, v186, v188
	s_waitcnt vmcnt(5)
	v_add_f32_e32 v190, v190, v191
	v_add_f32_e32 v192, v192, v193
	v_add_f32_e32 v224, v190, v192
	s_waitcnt vmcnt(4)
	v_add_f32_e32 v194, v194, v195
	v_add_f32_e32 v196, v196, v197
	v_add_f32_e32 v225, v194, v196
	ds_bpermute_b32 v249, v198, v222
	ds_bpermute_b32 v250, v198, v223
	ds_bpermute_b32 v251, v198, v224
	ds_bpermute_b32 v226, v198, v225
	s_waitcnt lgkmcnt(3)
	v_add_f32_e32 v222, v222, v249
	s_waitcnt lgkmcnt(2)
	v_add_f32_e32 v223, v223, v250
	s_waitcnt lgkmcnt(1)
	v_add_f32_e32 v224, v224, v251
	s_waitcnt lgkmcnt(0)
	v_add_f32_e32 v225, v225, v226
	ds_bpermute_b32 v249, v199, v222
	ds_bpermute_b32 v250, v199, v223
	ds_bpermute_b32 v251, v199, v224
	ds_bpermute_b32 v226, v199, v225
	s_waitcnt lgkmcnt(3)
	v_add_f32_e32 v222, v222, v249
	s_waitcnt lgkmcnt(2)
	v_add_f32_e32 v223, v223, v250
	s_waitcnt lgkmcnt(1)
	v_add_f32_e32 v224, v224, v251
	s_waitcnt lgkmcnt(0)
	v_add_f32_e32 v225, v225, v226
	v_fmamk_f32 v222, v222, 0x3a800000, v174
	v_fmamk_f32 v223, v223, 0x3a800000, v174
	v_fmamk_f32 v224, v224, 0x3a800000, v174
	v_fmamk_f32 v225, v225, 0x3a800000, v174
	v_rsq_f32_e32 v222, v222
	v_rsq_f32_e32 v223, v223
	v_rsq_f32_e32 v224, v224
	v_rsq_f32_e32 v225, v225
	s_mov_b32 s34, 0x3db8aa3b
	v_mul_f32_e32 v222, s34, v222
	v_mul_f32_e32 v223, s34, v223
	v_mul_f32_e32 v224, s34, v224
	v_mul_f32_e32 v225, s34, v225
	v_mul_f32_e32 v210, v210, v222
	v_mul_f32_e32 v212, v212, v223
	v_mul_f32_e32 v214, v214, v224
	v_mul_f32_e32 v216, v216, v225
	ds_bpermute_b32 v249, v198, v207
	ds_bpermute_b32 v250, v198, v209
	v_pk_fma_f32 v[60:61], v[60:61], v[222:223], v[210:211] op_sel:[0,0,0] op_sel_hi:[1,0,0] neg_lo:[0,0,1] neg_hi:[0,0,1]
	v_pk_fma_f32 v[62:63], v[62:63], v[222:223], v[210:211] op_sel:[0,0,0] op_sel_hi:[1,0,0] neg_lo:[0,0,1] neg_hi:[0,0,1]
	v_pk_fma_f32 v[56:57], v[56:57], v[222:223], v[210:211] op_sel:[0,0,0] op_sel_hi:[1,0,0] neg_lo:[0,0,1] neg_hi:[0,0,1]
	v_pk_fma_f32 v[58:59], v[58:59], v[222:223], v[210:211] op_sel:[0,0,0] op_sel_hi:[1,0,0] neg_lo:[0,0,1] neg_hi:[0,0,1]
	v_pk_fma_f32 v[52:53], v[52:53], v[222:223], v[210:211] op_sel:[0,0,0] op_sel_hi:[1,0,0] neg_lo:[0,0,1] neg_hi:[0,0,1]
	v_pk_fma_f32 v[54:55], v[54:55], v[222:223], v[210:211] op_sel:[0,0,0] op_sel_hi:[1,0,0] neg_lo:[0,0,1] neg_hi:[0,0,1]
	v_pk_fma_f32 v[48:49], v[48:49], v[222:223], v[210:211] op_sel:[0,0,0] op_sel_hi:[1,0,0] neg_lo:[0,0,1] neg_hi:[0,0,1]
	v_pk_fma_f32 v[50:51], v[50:51], v[222:223], v[210:211] op_sel:[0,0,0] op_sel_hi:[1,0,0] neg_lo:[0,0,1] neg_hi:[0,0,1]
	v_exp_f32_e32 v60, v60
	v_exp_f32_e32 v61, v61
	v_exp_f32_e32 v62, v62
	v_exp_f32_e32 v63, v63
	v_exp_f32_e32 v56, v56
	v_exp_f32_e32 v57, v57
	v_exp_f32_e32 v58, v58
	v_exp_f32_e32 v59, v59
	s_waitcnt lgkmcnt(1)
	v_add_f32_e32 v207, v207, v249
	s_waitcnt lgkmcnt(0)
	v_add_f32_e32 v209, v209, v250
	ds_bpermute_b32 v249, v199, v207
	ds_bpermute_b32 v250, v199, v209
	v_exp_f32_e32 v52, v52
	v_exp_f32_e32 v53, v53
	v_exp_f32_e32 v54, v54
	v_exp_f32_e32 v55, v55
	v_exp_f32_e32 v48, v48
	v_exp_f32_e32 v49, v49
	v_exp_f32_e32 v50, v50
	v_exp_f32_e32 v51, v51
	v_pk_add_f32 v[162:163], v[60:61], v[62:63]
	v_pk_add_f32 v[164:165], v[56:57], v[58:59]
	v_pk_add_f32 v[252:253], v[52:53], v[54:55]
	v_pk_add_f32 v[254:255], v[48:49], v[50:51]
	v_pk_add_f32 v[162:163], v[162:163], v[164:165]
	v_pk_add_f32 v[252:253], v[252:253], v[254:255]
	v_pk_add_f32 v[162:163], v[162:163], v[252:253]
	v_add_f32_e32 v211, v162, v163
	s_waitcnt lgkmcnt(1)
	v_add_f32_e32 v207, v207, v249
	s_waitcnt lgkmcnt(0)
	v_add_f32_e32 v209, v209, v250
	s_mov_b64 vcc, exec
	s_and_b64 exec, exec, s[0:1]
	ds_write_b64 v176, v[206:207]
	ds_write_b64 v177, v[208:209]
	s_mov_b64 exec, vcc
	v_pk_fma_f32 v[44:45], v[44:45], v[222:223], v[212:213] op_sel:[0,1,0] op_sel_hi:[1,1,0] neg_lo:[0,0,1] neg_hi:[0,0,1]
	v_pk_fma_f32 v[46:47], v[46:47], v[222:223], v[212:213] op_sel:[0,1,0] op_sel_hi:[1,1,0] neg_lo:[0,0,1] neg_hi:[0,0,1]
	v_pk_fma_f32 v[40:41], v[40:41], v[222:223], v[212:213] op_sel:[0,1,0] op_sel_hi:[1,1,0] neg_lo:[0,0,1] neg_hi:[0,0,1]
	v_pk_fma_f32 v[42:43], v[42:43], v[222:223], v[212:213] op_sel:[0,1,0] op_sel_hi:[1,1,0] neg_lo:[0,0,1] neg_hi:[0,0,1]
	v_pk_fma_f32 v[36:37], v[36:37], v[222:223], v[212:213] op_sel:[0,1,0] op_sel_hi:[1,1,0] neg_lo:[0,0,1] neg_hi:[0,0,1]
	v_pk_fma_f32 v[38:39], v[38:39], v[222:223], v[212:213] op_sel:[0,1,0] op_sel_hi:[1,1,0] neg_lo:[0,0,1] neg_hi:[0,0,1]
	v_pk_fma_f32 v[32:33], v[32:33], v[222:223], v[212:213] op_sel:[0,1,0] op_sel_hi:[1,1,0] neg_lo:[0,0,1] neg_hi:[0,0,1]
	v_pk_fma_f32 v[34:35], v[34:35], v[222:223], v[212:213] op_sel:[0,1,0] op_sel_hi:[1,1,0] neg_lo:[0,0,1] neg_hi:[0,0,1]
	v_exp_f32_e32 v44, v44
	v_exp_f32_e32 v45, v45
	v_exp_f32_e32 v46, v46
	v_exp_f32_e32 v47, v47
	v_exp_f32_e32 v40, v40
	v_exp_f32_e32 v41, v41
	v_exp_f32_e32 v42, v42
	v_exp_f32_e32 v43, v43
	s_waitcnt lgkmcnt(0)
	s_barrier
	ds_read_b128 v[146:149], v168 offset:1024
	ds_read_b128 v[150:153], v168 offset:1040
	ds_read_b128 v[154:157], v168 offset:1536
	ds_read_b128 v[158:161], v168 offset:1552
	v_exp_f32_e32 v36, v36
	v_exp_f32_e32 v37, v37
	v_exp_f32_e32 v38, v38
	v_exp_f32_e32 v39, v39
	v_exp_f32_e32 v32, v32
	v_exp_f32_e32 v33, v33
	v_exp_f32_e32 v34, v34
	v_exp_f32_e32 v35, v35
	v_pk_add_f32 v[162:163], v[44:45], v[46:47]
	v_pk_add_f32 v[164:165], v[40:41], v[42:43]
	v_pk_add_f32 v[252:253], v[36:37], v[38:39]
	v_pk_add_f32 v[254:255], v[32:33], v[34:35]
	v_pk_add_f32 v[162:163], v[162:163], v[164:165]
	v_pk_add_f32 v[252:253], v[252:253], v[254:255]
	v_pk_add_f32 v[162:163], v[162:163], v[252:253]
	v_add_f32_e32 v213, v162, v163
	s_waitcnt lgkmcnt(2)
	v_max3_f32 v227, v146, v148, v150
	v_max_f32_e32 v227, v227, v152
	v_sub_f32_e32 v146, v146, v227
	v_sub_f32_e32 v148, v148, v227
	v_sub_f32_e32 v150, v150, v227
	v_sub_f32_e32 v152, v152, v227
	v_sub_f32_e32 v206, v206, v227
	v_exp_f32_e32 v146, v146
	v_exp_f32_e32 v148, v148
	v_exp_f32_e32 v150, v150
	v_exp_f32_e32 v152, v152
	v_exp_f32_e32 v206, v206
	v_mul_f32_e32 v228, v147, v146
	v_mul_f32_e32 v226, v151, v150
	v_fmac_f32_e32 v228, v149, v148
	v_fmac_f32_e32 v226, v153, v152
	v_add_f32_e32 v228, v228, v226
	v_rcp_f32_e32 v228, v228
	s_nop 0
	v_mul_f32_e32 v206, v206, v228
	s_mov_b32 s34, 0x10000
	v_pk_mul_f32 v[92:93], v[92:93], v[206:207] op_sel:[0,0] op_sel_hi:[1,0]
	v_pk_mul_f32 v[94:95], v[94:95], v[206:207] op_sel:[0,0] op_sel_hi:[1,0]
	v_pk_mul_f32 v[88:89], v[88:89], v[206:207] op_sel:[0,0] op_sel_hi:[1,0]
	v_pk_mul_f32 v[90:91], v[90:91], v[206:207] op_sel:[0,0] op_sel_hi:[1,0]
	v_cvt_pk_bf16_f32 v92, v92, v93
	v_cvt_pk_bf16_f32 v93, v94, v95
	v_cvt_pk_bf16_f32 v94, v88, v89
	v_cvt_pk_bf16_f32 v95, v90, v91
	buffer_store_dwordx4 v[92:95], v229, s[16:19], s34 offen sc1
	v_pk_mul_f32 v[84:85], v[84:85], v[206:207] op_sel:[0,0] op_sel_hi:[1,0]
	v_pk_mul_f32 v[86:87], v[86:87], v[206:207] op_sel:[0,0] op_sel_hi:[1,0]
	v_pk_mul_f32 v[80:81], v[80:81], v[206:207] op_sel:[0,0] op_sel_hi:[1,0]
	v_pk_mul_f32 v[82:83], v[82:83], v[206:207] op_sel:[0,0] op_sel_hi:[1,0]
	v_cvt_pk_bf16_f32 v84, v84, v85
	v_cvt_pk_bf16_f32 v85, v86, v87
	v_cvt_pk_bf16_f32 v86, v80, v81
	v_cvt_pk_bf16_f32 v87, v82, v83
	buffer_store_dwordx4 v[84:87], v229, s[16:19], s34 offen offset:256 sc1
	s_waitcnt lgkmcnt(0)
	v_max3_f32 v227, v154, v156, v158
	v_max_f32_e32 v227, v227, v160
	v_sub_f32_e32 v154, v154, v227
	v_sub_f32_e32 v156, v156, v227
	v_sub_f32_e32 v158, v158, v227
	v_sub_f32_e32 v160, v160, v227
	v_sub_f32_e32 v208, v208, v227
	v_exp_f32_e32 v154, v154
	v_exp_f32_e32 v156, v156
	v_exp_f32_e32 v158, v158
	v_exp_f32_e32 v160, v160
	v_exp_f32_e32 v208, v208
	v_mul_f32_e32 v228, v155, v154
	v_mul_f32_e32 v226, v159, v158
	v_fmac_f32_e32 v228, v157, v156
	v_fmac_f32_e32 v226, v161, v160
	v_add_f32_e32 v228, v228, v226
	v_rcp_f32_e32 v228, v228
	s_nop 0
	v_mul_f32_e32 v208, v208, v228
	s_mov_b32 s34, 0x18000
	v_pk_mul_f32 v[76:77], v[76:77], v[208:209] op_sel:[0,0] op_sel_hi:[1,0]
	v_pk_mul_f32 v[78:79], v[78:79], v[208:209] op_sel:[0,0] op_sel_hi:[1,0]
	v_pk_mul_f32 v[72:73], v[72:73], v[208:209] op_sel:[0,0] op_sel_hi:[1,0]
	v_pk_mul_f32 v[74:75], v[74:75], v[208:209] op_sel:[0,0] op_sel_hi:[1,0]
	v_cvt_pk_bf16_f32 v76, v76, v77
	v_cvt_pk_bf16_f32 v77, v78, v79
	v_cvt_pk_bf16_f32 v78, v72, v73
	v_cvt_pk_bf16_f32 v79, v74, v75
	buffer_store_dwordx4 v[76:79], v229, s[16:19], s34 offen sc1
	v_pk_mul_f32 v[68:69], v[68:69], v[208:209] op_sel:[0,0] op_sel_hi:[1,0]
	v_pk_mul_f32 v[70:71], v[70:71], v[208:209] op_sel:[0,0] op_sel_hi:[1,0]
	v_pk_mul_f32 v[64:65], v[64:65], v[208:209] op_sel:[0,0] op_sel_hi:[1,0]
	v_pk_mul_f32 v[66:67], v[66:67], v[208:209] op_sel:[0,0] op_sel_hi:[1,0]
	v_cvt_pk_bf16_f32 v68, v68, v69
	v_cvt_pk_bf16_f32 v69, v70, v71
	v_cvt_pk_bf16_f32 v70, v64, v65
	v_cvt_pk_bf16_f32 v71, v66, v67
	buffer_store_dwordx4 v[68:71], v229, s[16:19], s34 offen offset:256 sc1
	ds_bpermute_b32 v249, v198, v211
	ds_bpermute_b32 v250, v198, v213
	v_pk_fma_f32 v[28:29], v[28:29], v[224:225], v[214:215] op_sel:[0,0,0] op_sel_hi:[1,0,0] neg_lo:[0,0,1] neg_hi:[0,0,1]
	v_pk_fma_f32 v[30:31], v[30:31], v[224:225], v[214:215] op_sel:[0,0,0] op_sel_hi:[1,0,0] neg_lo:[0,0,1] neg_hi:[0,0,1]
	v_pk_fma_f32 v[24:25], v[24:25], v[224:225], v[214:215] op_sel:[0,0,0] op_sel_hi:[1,0,0] neg_lo:[0,0,1] neg_hi:[0,0,1]
	v_pk_fma_f32 v[26:27], v[26:27], v[224:225], v[214:215] op_sel:[0,0,0] op_sel_hi:[1,0,0] neg_lo:[0,0,1] neg_hi:[0,0,1]
	v_pk_fma_f32 v[20:21], v[20:21], v[224:225], v[214:215] op_sel:[0,0,0] op_sel_hi:[1,0,0] neg_lo:[0,0,1] neg_hi:[0,0,1]
	v_pk_fma_f32 v[22:23], v[22:23], v[224:225], v[214:215] op_sel:[0,0,0] op_sel_hi:[1,0,0] neg_lo:[0,0,1] neg_hi:[0,0,1]
	v_pk_fma_f32 v[16:17], v[16:17], v[224:225], v[214:215] op_sel:[0,0,0] op_sel_hi:[1,0,0] neg_lo:[0,0,1] neg_hi:[0,0,1]
	v_pk_fma_f32 v[18:19], v[18:19], v[224:225], v[214:215] op_sel:[0,0,0] op_sel_hi:[1,0,0] neg_lo:[0,0,1] neg_hi:[0,0,1]
	v_exp_f32_e32 v28, v28
	v_exp_f32_e32 v29, v29
	v_exp_f32_e32 v30, v30
	v_exp_f32_e32 v31, v31
	v_exp_f32_e32 v24, v24
	v_exp_f32_e32 v25, v25
	v_exp_f32_e32 v26, v26
	v_exp_f32_e32 v27, v27
	s_waitcnt lgkmcnt(1)
	v_add_f32_e32 v211, v211, v249
	s_waitcnt lgkmcnt(0)
	v_add_f32_e32 v213, v213, v250
	ds_bpermute_b32 v249, v199, v211
	ds_bpermute_b32 v250, v199, v213
	v_exp_f32_e32 v20, v20
	v_exp_f32_e32 v21, v21
	v_exp_f32_e32 v22, v22
	v_exp_f32_e32 v23, v23
	v_exp_f32_e32 v16, v16
	v_exp_f32_e32 v17, v17
	v_exp_f32_e32 v18, v18
	v_exp_f32_e32 v19, v19
	v_pk_add_f32 v[162:163], v[28:29], v[30:31]
	v_pk_add_f32 v[164:165], v[24:25], v[26:27]
	v_pk_add_f32 v[252:253], v[20:21], v[22:23]
	v_pk_add_f32 v[254:255], v[16:17], v[18:19]
	v_pk_add_f32 v[162:163], v[162:163], v[164:165]
	v_pk_add_f32 v[252:253], v[252:253], v[254:255]
	v_pk_add_f32 v[162:163], v[162:163], v[252:253]
	v_add_f32_e32 v215, v162, v163
	s_waitcnt lgkmcnt(1)
	v_add_f32_e32 v211, v211, v249
	s_waitcnt lgkmcnt(0)
	v_add_f32_e32 v213, v213, v250
	s_mov_b64 vcc, exec
	s_and_b64 exec, exec, s[0:1]
	ds_write_b64 v178, v[210:211]
	ds_write_b64 v179, v[212:213]
	s_mov_b64 exec, vcc
	v_pk_fma_f32 v[12:13], v[12:13], v[224:225], v[216:217] op_sel:[0,1,0] op_sel_hi:[1,1,0] neg_lo:[0,0,1] neg_hi:[0,0,1]
	v_pk_fma_f32 v[14:15], v[14:15], v[224:225], v[216:217] op_sel:[0,1,0] op_sel_hi:[1,1,0] neg_lo:[0,0,1] neg_hi:[0,0,1]
	v_pk_fma_f32 v[8:9], v[8:9], v[224:225], v[216:217] op_sel:[0,1,0] op_sel_hi:[1,1,0] neg_lo:[0,0,1] neg_hi:[0,0,1]
	v_pk_fma_f32 v[10:11], v[10:11], v[224:225], v[216:217] op_sel:[0,1,0] op_sel_hi:[1,1,0] neg_lo:[0,0,1] neg_hi:[0,0,1]
	v_pk_fma_f32 v[4:5], v[4:5], v[224:225], v[216:217] op_sel:[0,1,0] op_sel_hi:[1,1,0] neg_lo:[0,0,1] neg_hi:[0,0,1]
	v_pk_fma_f32 v[6:7], v[6:7], v[224:225], v[216:217] op_sel:[0,1,0] op_sel_hi:[1,1,0] neg_lo:[0,0,1] neg_hi:[0,0,1]
	v_pk_fma_f32 v[0:1], v[0:1], v[224:225], v[216:217] op_sel:[0,1,0] op_sel_hi:[1,1,0] neg_lo:[0,0,1] neg_hi:[0,0,1]
	v_pk_fma_f32 v[2:3], v[2:3], v[224:225], v[216:217] op_sel:[0,1,0] op_sel_hi:[1,1,0] neg_lo:[0,0,1] neg_hi:[0,0,1]
	v_exp_f32_e32 v12, v12
	v_exp_f32_e32 v13, v13
	v_exp_f32_e32 v14, v14
	v_exp_f32_e32 v15, v15
	v_exp_f32_e32 v8, v8
	v_exp_f32_e32 v9, v9
	v_exp_f32_e32 v10, v10
	v_exp_f32_e32 v11, v11
	s_waitcnt lgkmcnt(0)
	s_barrier
	ds_read_b128 v[146:149], v168 offset:4096
	ds_read_b128 v[150:153], v168 offset:4112
	ds_read_b128 v[154:157], v168 offset:4608
	ds_read_b128 v[158:161], v168 offset:4624
	v_exp_f32_e32 v4, v4
	v_exp_f32_e32 v5, v5
	v_exp_f32_e32 v6, v6
	v_exp_f32_e32 v7, v7
	v_exp_f32_e32 v0, v0
	v_exp_f32_e32 v1, v1
	v_exp_f32_e32 v2, v2
	v_exp_f32_e32 v3, v3
	v_pk_add_f32 v[162:163], v[12:13], v[14:15]
	v_pk_add_f32 v[164:165], v[8:9], v[10:11]
	v_pk_add_f32 v[252:253], v[4:5], v[6:7]
	v_pk_add_f32 v[254:255], v[0:1], v[2:3]
	v_pk_add_f32 v[162:163], v[162:163], v[164:165]
	v_pk_add_f32 v[252:253], v[252:253], v[254:255]
	v_pk_add_f32 v[162:163], v[162:163], v[252:253]
	v_add_f32_e32 v217, v162, v163
	s_waitcnt lgkmcnt(2)
	v_max3_f32 v227, v146, v148, v150
	v_max_f32_e32 v227, v227, v152
	v_sub_f32_e32 v146, v146, v227
	v_sub_f32_e32 v148, v148, v227
	v_sub_f32_e32 v150, v150, v227
	v_sub_f32_e32 v152, v152, v227
	v_sub_f32_e32 v210, v210, v227
	v_exp_f32_e32 v146, v146
	v_exp_f32_e32 v148, v148
	v_exp_f32_e32 v150, v150
	v_exp_f32_e32 v152, v152
	v_exp_f32_e32 v210, v210
	v_mul_f32_e32 v228, v147, v146
	v_mul_f32_e32 v226, v151, v150
	v_fmac_f32_e32 v228, v149, v148
	v_fmac_f32_e32 v226, v153, v152
	v_add_f32_e32 v228, v228, v226
	v_rcp_f32_e32 v228, v228
	s_nop 0
	v_mul_f32_e32 v210, v210, v228
	s_mov_b32 s34, 0x40000
	v_pk_mul_f32 v[60:61], v[60:61], v[210:211] op_sel:[0,0] op_sel_hi:[1,0]
	v_pk_mul_f32 v[62:63], v[62:63], v[210:211] op_sel:[0,0] op_sel_hi:[1,0]
	v_pk_mul_f32 v[56:57], v[56:57], v[210:211] op_sel:[0,0] op_sel_hi:[1,0]
	v_pk_mul_f32 v[58:59], v[58:59], v[210:211] op_sel:[0,0] op_sel_hi:[1,0]
	v_cvt_pk_bf16_f32 v60, v60, v61
	v_cvt_pk_bf16_f32 v61, v62, v63
	v_cvt_pk_bf16_f32 v62, v56, v57
	v_cvt_pk_bf16_f32 v63, v58, v59
	buffer_store_dwordx4 v[60:63], v229, s[16:19], s34 offen sc1
	v_pk_mul_f32 v[52:53], v[52:53], v[210:211] op_sel:[0,0] op_sel_hi:[1,0]
	v_pk_mul_f32 v[54:55], v[54:55], v[210:211] op_sel:[0,0] op_sel_hi:[1,0]
	v_pk_mul_f32 v[48:49], v[48:49], v[210:211] op_sel:[0,0] op_sel_hi:[1,0]
	v_pk_mul_f32 v[50:51], v[50:51], v[210:211] op_sel:[0,0] op_sel_hi:[1,0]
	v_cvt_pk_bf16_f32 v52, v52, v53
	v_cvt_pk_bf16_f32 v53, v54, v55
	v_cvt_pk_bf16_f32 v54, v48, v49
	v_cvt_pk_bf16_f32 v55, v50, v51
	buffer_store_dwordx4 v[52:55], v229, s[16:19], s34 offen offset:256 sc1
	s_waitcnt lgkmcnt(0)
	v_max3_f32 v227, v154, v156, v158
	v_max_f32_e32 v227, v227, v160
	v_sub_f32_e32 v154, v154, v227
	v_sub_f32_e32 v156, v156, v227
	v_sub_f32_e32 v158, v158, v227
	v_sub_f32_e32 v160, v160, v227
	v_sub_f32_e32 v212, v212, v227
	v_exp_f32_e32 v154, v154
	v_exp_f32_e32 v156, v156
	v_exp_f32_e32 v158, v158
	v_exp_f32_e32 v160, v160
	v_exp_f32_e32 v212, v212
	v_mul_f32_e32 v228, v155, v154
	v_mul_f32_e32 v226, v159, v158
	v_fmac_f32_e32 v228, v157, v156
	v_fmac_f32_e32 v226, v161, v160
	v_add_f32_e32 v228, v228, v226
	v_rcp_f32_e32 v228, v228
	s_nop 0
	v_mul_f32_e32 v212, v212, v228
	s_mov_b32 s34, 0x48000
	v_pk_mul_f32 v[44:45], v[44:45], v[212:213] op_sel:[0,0] op_sel_hi:[1,0]
	v_pk_mul_f32 v[46:47], v[46:47], v[212:213] op_sel:[0,0] op_sel_hi:[1,0]
	v_pk_mul_f32 v[40:41], v[40:41], v[212:213] op_sel:[0,0] op_sel_hi:[1,0]
	v_pk_mul_f32 v[42:43], v[42:43], v[212:213] op_sel:[0,0] op_sel_hi:[1,0]
	v_cvt_pk_bf16_f32 v44, v44, v45
	v_cvt_pk_bf16_f32 v45, v46, v47
	v_cvt_pk_bf16_f32 v46, v40, v41
	v_cvt_pk_bf16_f32 v47, v42, v43
	buffer_store_dwordx4 v[44:47], v229, s[16:19], s34 offen sc1
	v_pk_mul_f32 v[36:37], v[36:37], v[212:213] op_sel:[0,0] op_sel_hi:[1,0]
	v_pk_mul_f32 v[38:39], v[38:39], v[212:213] op_sel:[0,0] op_sel_hi:[1,0]
	v_pk_mul_f32 v[32:33], v[32:33], v[212:213] op_sel:[0,0] op_sel_hi:[1,0]
	v_pk_mul_f32 v[34:35], v[34:35], v[212:213] op_sel:[0,0] op_sel_hi:[1,0]
	v_cvt_pk_bf16_f32 v36, v36, v37
	v_cvt_pk_bf16_f32 v37, v38, v39
	v_cvt_pk_bf16_f32 v38, v32, v33
	v_cvt_pk_bf16_f32 v39, v34, v35
	buffer_store_dwordx4 v[36:39], v229, s[16:19], s34 offen offset:256 sc1
	ds_bpermute_b32 v249, v198, v215
	ds_bpermute_b32 v250, v198, v217
	s_waitcnt lgkmcnt(1)
	v_add_f32_e32 v215, v215, v249
	s_waitcnt lgkmcnt(0)
	v_add_f32_e32 v217, v217, v250
	ds_bpermute_b32 v249, v199, v215
	ds_bpermute_b32 v250, v199, v217
	s_waitcnt lgkmcnt(1)
	v_add_f32_e32 v215, v215, v249
	s_waitcnt lgkmcnt(0)
	v_add_f32_e32 v217, v217, v250
	s_mov_b64 vcc, exec
	s_and_b64 exec, exec, s[0:1]
	ds_write_b64 v180, v[214:215]
	ds_write_b64 v181, v[216:217]
	s_mov_b64 exec, vcc
	s_waitcnt lgkmcnt(0)
	s_barrier
	ds_read_b128 v[146:149], v168 offset:5120
	ds_read_b128 v[150:153], v168 offset:5136
	ds_read_b128 v[154:157], v168 offset:5632
	ds_read_b128 v[158:161], v168 offset:5648
	s_waitcnt lgkmcnt(2)
	v_max3_f32 v227, v146, v148, v150
	v_max_f32_e32 v227, v227, v152
	v_sub_f32_e32 v146, v146, v227
	v_sub_f32_e32 v148, v148, v227
	v_sub_f32_e32 v150, v150, v227
	v_sub_f32_e32 v152, v152, v227
	v_sub_f32_e32 v214, v214, v227
	v_exp_f32_e32 v146, v146
	v_exp_f32_e32 v148, v148
	v_exp_f32_e32 v150, v150
	v_exp_f32_e32 v152, v152
	v_exp_f32_e32 v214, v214
	v_mul_f32_e32 v228, v147, v146
	v_mul_f32_e32 v226, v151, v150
	v_fmac_f32_e32 v228, v149, v148
	v_fmac_f32_e32 v226, v153, v152
	v_add_f32_e32 v228, v228, v226
	v_rcp_f32_e32 v228, v228
	s_nop 0
	v_mul_f32_e32 v214, v214, v228
	s_mov_b32 s34, 0x50000
	v_pk_mul_f32 v[28:29], v[28:29], v[214:215] op_sel:[0,0] op_sel_hi:[1,0]
	v_pk_mul_f32 v[30:31], v[30:31], v[214:215] op_sel:[0,0] op_sel_hi:[1,0]
	v_pk_mul_f32 v[24:25], v[24:25], v[214:215] op_sel:[0,0] op_sel_hi:[1,0]
	v_pk_mul_f32 v[26:27], v[26:27], v[214:215] op_sel:[0,0] op_sel_hi:[1,0]
	v_cvt_pk_bf16_f32 v28, v28, v29
	v_cvt_pk_bf16_f32 v29, v30, v31
	v_cvt_pk_bf16_f32 v30, v24, v25
	v_cvt_pk_bf16_f32 v31, v26, v27
	buffer_store_dwordx4 v[28:31], v229, s[16:19], s34 offen sc1
	v_pk_mul_f32 v[20:21], v[20:21], v[214:215] op_sel:[0,0] op_sel_hi:[1,0]
	v_pk_mul_f32 v[22:23], v[22:23], v[214:215] op_sel:[0,0] op_sel_hi:[1,0]
	v_pk_mul_f32 v[16:17], v[16:17], v[214:215] op_sel:[0,0] op_sel_hi:[1,0]
	v_pk_mul_f32 v[18:19], v[18:19], v[214:215] op_sel:[0,0] op_sel_hi:[1,0]
	v_cvt_pk_bf16_f32 v20, v20, v21
	v_cvt_pk_bf16_f32 v21, v22, v23
	v_cvt_pk_bf16_f32 v22, v16, v17
	v_cvt_pk_bf16_f32 v23, v18, v19
	buffer_store_dwordx4 v[20:23], v229, s[16:19], s34 offen offset:256 sc1
	s_waitcnt lgkmcnt(0)
	v_max3_f32 v227, v154, v156, v158
	v_max_f32_e32 v227, v227, v160
	v_sub_f32_e32 v154, v154, v227
	v_sub_f32_e32 v156, v156, v227
	v_sub_f32_e32 v158, v158, v227
	v_sub_f32_e32 v160, v160, v227
	v_sub_f32_e32 v216, v216, v227
	v_exp_f32_e32 v154, v154
	v_exp_f32_e32 v156, v156
	v_exp_f32_e32 v158, v158
	v_exp_f32_e32 v160, v160
	v_exp_f32_e32 v216, v216
	v_mul_f32_e32 v228, v155, v154
	v_mul_f32_e32 v226, v159, v158
	v_fmac_f32_e32 v228, v157, v156
	v_fmac_f32_e32 v226, v161, v160
	v_add_f32_e32 v228, v228, v226
	v_rcp_f32_e32 v228, v228
	s_nop 0
	v_mul_f32_e32 v216, v216, v228
	s_mov_b32 s34, 0x58000
	v_pk_mul_f32 v[12:13], v[12:13], v[216:217] op_sel:[0,0] op_sel_hi:[1,0]
	v_pk_mul_f32 v[14:15], v[14:15], v[216:217] op_sel:[0,0] op_sel_hi:[1,0]
	v_pk_mul_f32 v[8:9], v[8:9], v[216:217] op_sel:[0,0] op_sel_hi:[1,0]
	v_pk_mul_f32 v[10:11], v[10:11], v[216:217] op_sel:[0,0] op_sel_hi:[1,0]
	v_cvt_pk_bf16_f32 v12, v12, v13
	v_cvt_pk_bf16_f32 v13, v14, v15
	v_cvt_pk_bf16_f32 v14, v8, v9
	v_cvt_pk_bf16_f32 v15, v10, v11
	buffer_store_dwordx4 v[12:15], v229, s[16:19], s34 offen sc1
	v_pk_mul_f32 v[4:5], v[4:5], v[216:217] op_sel:[0,0] op_sel_hi:[1,0]
	v_pk_mul_f32 v[6:7], v[6:7], v[216:217] op_sel:[0,0] op_sel_hi:[1,0]
	v_pk_mul_f32 v[0:1], v[0:1], v[216:217] op_sel:[0,0] op_sel_hi:[1,0]
	v_pk_mul_f32 v[2:3], v[2:3], v[216:217] op_sel:[0,0] op_sel_hi:[1,0]
	v_cvt_pk_bf16_f32 v4, v4, v5
	v_cvt_pk_bf16_f32 v5, v6, v7
	v_cvt_pk_bf16_f32 v6, v0, v1
	v_cvt_pk_bf16_f32 v7, v2, v3
	buffer_store_dwordx4 v[4:7], v229, s[16:19], s34 offen offset:256 sc1
	s_waitcnt lgkmcnt(0)
	s_andn2_b64 vcc, exec, s[4:5]
	s_mov_b64 s[4:5], -1
	s_cbranch_vccnz .LBB0_506
	s_andn2_b64 vcc, exec, s[6:7]
	s_cbranch_vccnz .LBB0_505
	s_barrier
	s_branch .LBB0_505
